# gate GEMM epilogue: eight serialized row-sum loads issued together with one wait
# speedup vs baseline: 1.0158x; 1.0035x over previous
; __device__ __forceinline__ float sigmoidf_(float v) { return __builtin_amdgcn_rcpf(1.0f + __expf(-v)); }
; __device__ __forceinline__ int ltid(int wv) { unsigned z = 0u; asm volatile("" : "+v"(z)); return wv * 64 + (int)__builtin_amdgcn_mbcnt_hi(~0u, __builtin_amdgcn_mbcnt_lo(~0u, z)); }
; #define EPI_LOOP_ROWS for (int ai = 0; ai < 2; ++ai) _Pragma("unroll") for (int m = 0; m < 4; ++m)
; __device__ __forceinline__ float row_part(const float* RS, int row, int fq) { const f32x4 a = ((const f32x4*)(RS + (size_t)row * 16))[fq]; return (a.x + a.y) + (a.z + a.w); }
; __device__ __forceinline__ float row_rstd_fin(float s, int lane) { s += shx(s, 16, lane); s += shx(s, 32, lane); return rsqrtf(s * (1.0f / 1024.0f) + EPS); }
;     __device__ __forceinline__ void operator()(const f32x4 (&acc)[2][2][4][2], const Unit& u, int wv) const {
;         const int t_ = ltid(wv), wid_ = __builtin_amdgcn_readfirstlane(t_ >> 6), wr = wid_ >> 2, wc = wid_ & 3, fr = t_ & 15, fq = (t_ & 63) >> 4;
;         const int col0 = u.pn * BM + wc * 32 + 8 * fq, row0 = u.pm * BM + wr * 64 + fr;
;         float rs[2][4], sq[2][4];
; #pragma unroll
;         EPI_LOOP_ROWS rs[ai][m] = RSin ? row_part(RSin, row0 + ai * HALF + m * 16, fq) : 0.f;
; #pragma unroll
;         EPI_LOOP_ROWS rs[ai][m] = RSin ? row_rstd_fin(rs[ai][m], t_ & 63) : 1.0f;
; #pragma unroll
;         EPI_LOOP_ROWS { const size_t row = (size_t)(row0 + ai * HALF + m * 16);
;             const float rstd = rs[ai][m]; float ssq = 0.f;
; #pragma unroll
;             for (int bj = 0; bj < 2; ++bj) { const int col = col0 + bj * HALF;
;                 f32x4 v0 = acc[ai][bj][m][0] * rstd, v1 = acc[ai][bj][m][1] * rstd;
;                 if (PP) { const u32x4 g = *(const u32x4*)(PP + row * 1024 + col);
;                     v0[0] = sigmoidf_(v0[0]) * __builtin_bit_cast(float, g.x << 16); v0[1] = sigmoidf_(v0[1]) * __builtin_bit_cast(float, g.x & 0xffff0000u);
;                     v0[2] = sigmoidf_(v0[2]) * __builtin_bit_cast(float, g.y << 16); v0[3] = sigmoidf_(v0[3]) * __builtin_bit_cast(float, g.y & 0xffff0000u);
;                     v1[0] = sigmoidf_(v1[0]) * __builtin_bit_cast(float, g.z << 16); v1[1] = sigmoidf_(v1[1]) * __builtin_bit_cast(float, g.z & 0xffff0000u);
;                     v1[2] = sigmoidf_(v1[2]) * __builtin_bit_cast(float, g.w << 16); v1[3] = sigmoidf_(v1[3]) * __builtin_bit_cast(float, g.w & 0xffff0000u); }
.LBB0_144:
	v_mov_b32_e32 v0, v1
	s_lshl_b32 s1, s4, 8
	v_mbcnt_lo_u32_b32 v0, -1, v0
	v_mbcnt_hi_u32_b32 v0, -1, v0
	v_add_u32_e32 v142, s33, v0
	v_and_b32_e32 v214, 63, v0
	v_readfirstlane_b32 s0, v142
	s_bfe_u32 s49, s0, 0x20006
	s_ashr_i32 s0, s0, 2
	s_andn2_b32 s0, s0, 63
	s_add_i32 s0, s0, s1
	v_and_or_b32 v164, v0, 15, s0
	v_lshrrev_b32_e32 v196, 1, v0
	v_and_b32_e32 v0, 48, v0
	v_ashrrev_i32_e32 v165, 31, v164
	v_lshl_add_u64 v[190:191], s[64:65], 0, v[0:1]
	v_or_b32_e32 v186, 16, v164
	v_ashrrev_i32_e32 v187, 31, v186
	v_or_b32_e32 v180, 32, v164
	v_ashrrev_i32_e32 v181, 31, v180
	v_or_b32_e32 v178, 48, v164
	v_ashrrev_i32_e32 v179, 31, v178
	v_add_u32_e32 v172, 0x80, v164
	v_ashrrev_i32_e32 v173, 31, v172
	v_add_u32_e32 v168, 0x90, v164
	v_ashrrev_i32_e32 v169, 31, v168
	v_add_u32_e32 v162, 0xa0, v164
	v_ashrrev_i32_e32 v163, 31, v162
	v_add_u32_e32 v158, 0xb0, v164
	v_ashrrev_i32_e32 v159, 31, v158
	v_lshlrev_b64 v[142:143], 6, v[164:165]
	v_lshl_add_u64 v[250:251], v[190:191], 0, v[142:143]
	global_load_dwordx4 v[232:235], v[250:251], off
	v_lshlrev_b64 v[144:145], 6, v[186:187]
	v_lshl_add_u64 v[250:251], v[190:191], 0, v[144:145]
	global_load_dwordx4 v[236:239], v[250:251], off
	v_lshlrev_b64 v[146:147], 6, v[180:181]
	v_lshl_add_u64 v[250:251], v[190:191], 0, v[146:147]
	global_load_dwordx4 v[240:243], v[250:251], off
	v_lshlrev_b64 v[148:149], 6, v[178:179]
	v_lshl_add_u64 v[250:251], v[190:191], 0, v[148:149]
	global_load_dwordx4 v[244:247], v[250:251], off
	v_lshlrev_b64 v[150:151], 6, v[172:173]
	v_lshl_add_u64 v[250:251], v[190:191], 0, v[150:151]
	global_load_dwordx4 v[202:205], v[250:251], off
	v_lshlrev_b64 v[152:153], 6, v[168:169]
	v_lshl_add_u64 v[250:251], v[190:191], 0, v[152:153]
	global_load_dwordx4 v[206:209], v[250:251], off
	v_lshlrev_b64 v[154:155], 6, v[162:163]
	v_lshl_add_u64 v[250:251], v[190:191], 0, v[154:155]
	global_load_dwordx4 v[210:213], v[250:251], off
	v_lshlrev_b64 v[156:157], 6, v[158:159]
	v_lshl_add_u64 v[250:251], v[190:191], 0, v[156:157]
	global_load_dwordx4 v[198:201], v[250:251], off
	v_lshlrev_b32_e32 v0, 2, v214
	v_xor_b32_e32 v216, 64, v0
	v_xor_b32_e32 v215, 0x80, v0
	s_lshl_b32 s5, s49, 5
	s_lshl_b32 s0, s28, 8
	s_or_b32 s10, s5, s0
	s_mov_b32 s0, 0x358637bd
	v_and_or_b32 v196, v196, 24, s10
	v_ashrrev_i32_e32 v197, 31, v196
	v_lshlrev_b32_e32 v217, 11, v164
	v_lshl_add_u32 v217, v196, 1, v217
	global_load_dwordx4 v[220:223], v217, s[12:13]
	s_waitcnt vmcnt(0)
	v_add_f32_e32 v160, v233, v232
	v_add_f32_e32 v161, v234, v235
	v_add_f32_e32 v182, v237, v236
	v_add_f32_e32 v183, v238, v239
	v_add_f32_e32 v174, v241, v240
	v_add_f32_e32 v175, v242, v243
	v_add_f32_e32 v176, v245, v244
	v_add_f32_e32 v177, v246, v247
	v_add_f32_e32 v170, v203, v202
	v_add_f32_e32 v171, v204, v205
	v_add_f32_e32 v192, v207, v206
	v_add_f32_e32 v193, v208, v209
	v_add_f32_e32 v166, v211, v210
	v_add_f32_e32 v167, v212, v213
	v_add_f32_e32 v190, v199, v198
	v_add_f32_e32 v191, v200, v201
	v_mov_b32_e32 v198, v182
	v_mov_b32_e32 v199, v160
	v_mov_b32_e32 v160, v183
	v_pk_add_f32 v[160:161], v[198:199], v[160:161]
	ds_bpermute_b32 v183, v216, v161
	ds_bpermute_b32 v182, v216, v160
	v_mov_b64_e32 v[198:199], s[0:1]
	s_mov_b32 s0, 0x3a800000
	s_waitcnt lgkmcnt(0)
	v_pk_add_f32 v[160:161], v[160:161], v[182:183]
	ds_bpermute_b32 v183, v215, v161
	ds_bpermute_b32 v182, v215, v160
	s_waitcnt lgkmcnt(0)
	v_pk_add_f32 v[160:161], v[160:161], v[182:183]
	s_nop 0
	v_pk_fma_f32 v[160:161], v[160:161], s[0:1], v[198:199] op_sel_hi:[1,0,0]
	s_nop 0
	v_mul_f32_e32 v0, 0x4b800000, v161
	v_cmp_gt_f32_e64 s[4:5], s97, v161
	v_cmp_gt_f32_e32 vcc, s97, v160
	s_nop 0
	v_cndmask_b32_e64 v0, v161, v0, s[4:5]
	v_rsq_f32_e32 v0, v0
	s_nop 0
	v_mul_f32_e32 v161, 0x45800000, v0
	v_cndmask_b32_e64 v188, v0, v161, s[4:5]
	v_mul_f32_e32 v0, 0x4b800000, v160
	v_cndmask_b32_e32 v0, v160, v0, vcc
	v_rsq_f32_e32 v0, v0
	v_mov_b32_e32 v161, v174
	v_mov_b32_e32 v174, v177
	v_pk_mul_f32 v[204:205], v[122:123], v[188:189] op_sel_hi:[1,0]
	v_mul_f32_e32 v160, 0x45800000, v0
	v_cndmask_b32_e32 v184, v0, v160, vcc
	v_mov_b32_e32 v160, v176
	v_pk_add_f32 v[160:161], v[160:161], v[174:175]
	ds_bpermute_b32 v175, v216, v161
	ds_bpermute_b32 v174, v216, v160
	v_pk_mul_f32 v[210:211], v[124:125], v[188:189] op_sel_hi:[1,0]
	v_pk_mul_f32 v[128:129], v[128:129], v[188:189] op_sel_hi:[1,0]
	v_pk_mul_f32 v[126:127], v[126:127], v[188:189] op_sel_hi:[1,0]
	v_pk_mul_f32 v[120:121], v[120:121], v[188:189] op_sel_hi:[1,0]
	s_waitcnt lgkmcnt(0)
	v_pk_add_f32 v[160:161], v[160:161], v[174:175]
	ds_bpermute_b32 v175, v215, v161
	ds_bpermute_b32 v174, v215, v160
	v_mul_f32_e32 v126, 0xbfb8aa3b, v126
	v_exp_f32_e32 v126, v126
	v_pk_mul_f32 v[118:119], v[118:119], v[188:189] op_sel_hi:[1,0]
	v_pk_mul_f32 v[110:111], v[110:111], v[184:185] op_sel_hi:[1,0]
	s_waitcnt lgkmcnt(0)
	v_pk_add_f32 v[160:161], v[160:161], v[174:175]
	v_add_f32_e32 v126, 1.0, v126
	v_pk_fma_f32 v[160:161], v[160:161], s[0:1], v[198:199] op_sel_hi:[1,0,0]
	v_mul_f32_e32 v118, 0xbfb8aa3b, v118
	v_mul_f32_e32 v0, 0x4b800000, v161
	v_cmp_gt_f32_e64 s[4:5], s97, v161
	v_cmp_gt_f32_e32 vcc, s97, v160
	v_exp_f32_e32 v118, v118
	v_cndmask_b32_e64 v0, v161, v0, s[4:5]
	v_rsq_f32_e32 v0, v0
	v_pk_mul_f32 v[112:113], v[112:113], v[184:185] op_sel_hi:[1,0]
	v_add_f32_e32 v118, 1.0, v118
	v_mul_f32_e32 v112, 0xbfb8aa3b, v112
	v_mul_f32_e32 v161, 0x45800000, v0
	v_cndmask_b32_e64 v182, v0, v161, s[4:5]
	v_mul_f32_e32 v0, 0x4b800000, v160
	v_cndmask_b32_e32 v0, v160, v0, vcc
	v_rsq_f32_e32 v0, v0
	v_mov_b32_e32 v161, v170
	v_mov_b32_e32 v170, v193
	v_mul_f32_e32 v113, 0xbfb8aa3b, v113
	v_mul_f32_e32 v160, 0x45800000, v0
	v_cndmask_b32_e32 v176, v0, v160, vcc
	v_mov_b32_e32 v160, v192
	v_pk_add_f32 v[160:161], v[160:161], v[170:171]
	ds_bpermute_b32 v171, v216, v161
	ds_bpermute_b32 v170, v216, v160
	v_lshlrev_b64 v[192:193], 11, v[164:165]
	v_lshl_add_u64 v[122:123], s[12:13], 0, v[192:193]
	v_exp_f32_e32 v112, v112
	v_exp_f32_e32 v113, v113
	s_waitcnt lgkmcnt(0)
; __device__ __forceinline__ float sigmoidf_(float v) { return __builtin_amdgcn_rcpf(1.0f + __expf(-v)); }
; #define EPI_LOOP_ROWS for (int ai = 0; ai < 2; ++ai) _Pragma("unroll") for (int m = 0; m < 4; ++m)
; __device__ __forceinline__ float row_part(const float* RS, int row, int fq) { const f32x4 a = ((const f32x4*)(RS + (size_t)row * 16))[fq]; return (a.x + a.y) + (a.z + a.w); }
; __device__ __forceinline__ float row_rstd_fin(float s, int lane) { s += shx(s, 16, lane); s += shx(s, 32, lane); return rsqrtf(s * (1.0f / 1024.0f) + EPS); }
;     __device__ __forceinline__ void operator()(const f32x4 (&acc)[2][2][4][2], const Unit& u, int wv) const {
;     ...
;         EPI_LOOP_ROWS rs[ai][m] = RSin ? row_part(RSin, row0 + ai * HALF + m * 16, fq) : 0.f;
; #pragma unroll
;         EPI_LOOP_ROWS rs[ai][m] = RSin ? row_rstd_fin(rs[ai][m], t_ & 63) : 1.0f;
; #pragma unroll
;         EPI_LOOP_ROWS { const size_t row = (size_t)(row0 + ai * HALF + m * 16);
;             const float rstd = rs[ai][m]; float ssq = 0.f;
; #pragma unroll
;             for (int bj = 0; bj < 2; ++bj) { const int col = col0 + bj * HALF;
;                 f32x4 v0 = acc[ai][bj][m][0] * rstd, v1 = acc[ai][bj][m][1] * rstd;
;                 if (PP) { const u32x4 g = *(const u32x4*)(PP + row * 1024 + col);
;                     v0[0] = sigmoidf_(v0[0]) * __builtin_bit_cast(float, g.x << 16); v0[1] = sigmoidf_(v0[1]) * __builtin_bit_cast(float, g.x & 0xffff0000u);
;                     v0[2] = sigmoidf_(v0[2]) * __builtin_bit_cast(float, g.y << 16); v0[3] = sigmoidf_(v0[3]) * __builtin_bit_cast(float, g.y & 0xffff0000u);
;                     v1[0] = sigmoidf_(v1[0]) * __builtin_bit_cast(float, g.z << 16); v1[1] = sigmoidf_(v1[1]) * __builtin_bit_cast(float, g.z & 0xffff0000u);
;                     v1[2] = sigmoidf_(v1[2]) * __builtin_bit_cast(float, g.w << 16); v1[3] = sigmoidf_(v1[3]) * __builtin_bit_cast(float, g.w & 0xffff0000u); }
;                 float* xp = X + row * 1024 + col;
;                 v0 += *(const f32x4*)xp; v1 += *(const f32x4*)(xp + 4);
	v_pk_add_f32 v[160:161], v[160:161], v[170:171]
	ds_bpermute_b32 v171, v215, v161
	ds_bpermute_b32 v170, v215, v160
	v_add_f32_e32 v112, 1.0, v112
	v_add_f32_e32 v113, 1.0, v113
	v_rcp_f32_e32 v112, v112
	v_rcp_f32_e32 v113, v113
	s_waitcnt lgkmcnt(0)
	v_pk_add_f32 v[160:161], v[160:161], v[170:171]
	v_pk_mul_f32 v[104:105], v[104:105], v[184:185] op_sel_hi:[1,0]
	v_pk_fma_f32 v[160:161], v[160:161], s[0:1], v[198:199] op_sel_hi:[1,0,0]
	v_pk_mul_f32 v[102:103], v[102:103], v[184:185] op_sel_hi:[1,0]
	v_mul_f32_e32 v0, 0x4b800000, v161
	v_cmp_gt_f32_e64 s[4:5], s97, v161
	v_cmp_gt_f32_e32 vcc, s97, v160
	v_mul_f32_e32 v102, 0xbfb8aa3b, v102
	v_cndmask_b32_e64 v0, v161, v0, s[4:5]
	v_rsq_f32_e32 v0, v0
	v_exp_f32_e32 v102, v102
	v_pk_mul_f32 v[90:91], v[90:91], v[182:183] op_sel_hi:[1,0]
	v_pk_mul_f32 v[94:95], v[94:95], v[182:183] op_sel_hi:[1,0]
	v_mul_f32_e32 v161, 0x45800000, v0
	v_cndmask_b32_e64 v174, v0, v161, s[4:5]
	v_mul_f32_e32 v0, 0x4b800000, v160
	v_cndmask_b32_e32 v0, v160, v0, vcc
	v_rsq_f32_e32 v0, v0
	v_mov_b32_e32 v161, v166
	v_mov_b32_e32 v166, v191
	v_add_f32_e32 v102, 1.0, v102
	v_mul_f32_e32 v160, 0x45800000, v0
	v_cndmask_b32_e32 v170, v0, v160, vcc
	v_mov_b32_e32 v160, v190
	v_pk_add_f32 v[160:161], v[160:161], v[166:167]
	ds_bpermute_b32 v167, v216, v161
	ds_bpermute_b32 v166, v216, v160
	v_mul_f32_e32 v90, 0xbfb8aa3b, v90
	v_exp_f32_e32 v90, v90
	v_mul_f32_e32 v94, 0xbfb8aa3b, v94
	v_exp_f32_e32 v94, v94
	s_waitcnt lgkmcnt(0)
	v_pk_add_f32 v[160:161], v[160:161], v[166:167]
	ds_bpermute_b32 v167, v215, v161
	ds_bpermute_b32 v166, v215, v160
	v_add_f32_e32 v90, 1.0, v90
	v_add_f32_e32 v94, 1.0, v94
	v_pk_mul_f32 v[92:93], v[92:93], v[182:183] op_sel_hi:[1,0]
	v_pk_mul_f32 v[96:97], v[96:97], v[182:183] op_sel_hi:[1,0]
	s_waitcnt lgkmcnt(0)
	v_pk_add_f32 v[160:161], v[160:161], v[166:167]
	v_pk_mul_f32 v[88:89], v[88:89], v[182:183] op_sel_hi:[1,0]
	v_pk_fma_f32 v[160:161], v[160:161], s[0:1], v[198:199] op_sel_hi:[1,0,0]
	v_rcp_f32_e32 v198, v126
	v_mul_f32_e32 v0, 0x4b800000, v161
	v_cmp_gt_f32_e64 s[4:5], s97, v161
	v_cmp_gt_f32_e32 vcc, s97, v160
	v_mul_f32_e32 v126, 0xbfb8aa3b, v127
	v_cndmask_b32_e64 v0, v161, v0, s[4:5]
	v_rsq_f32_e32 v0, v0
	v_exp_f32_e32 v126, v126
	v_pk_mul_f32 v[86:87], v[86:87], v[182:183] op_sel_hi:[1,0]
	v_pk_mul_f32 v[78:79], v[78:79], v[176:177] op_sel_hi:[1,0]
	v_mul_f32_e32 v161, 0x45800000, v0
	v_cndmask_b32_e64 v166, v0, v161, s[4:5]
	v_mul_f32_e32 v0, 0x4b800000, v160
	v_cndmask_b32_e32 v0, v160, v0, vcc
	v_rsq_f32_e32 v0, v0
	v_add_f32_e32 v126, 1.0, v126
	v_rcp_f32_e32 v199, v126
	v_mul_f32_e32 v86, 0xbfb8aa3b, v86
	v_mul_f32_e32 v160, 0x45800000, v0
	v_cndmask_b32_e32 v0, v0, v160, vcc
	v_lshlrev_b64 v[160:161], 1, v[196:197]
	v_lshl_add_u64 v[190:191], v[122:123], 0, v[160:161]
	v_mov_b32_e32 v122, v220
	v_mov_b32_e32 v123, v221
	v_mov_b32_e32 v124, v222
	v_mov_b32_e32 v125, v223
	v_exp_f32_e32 v86, v86
	v_pk_mul_f32 v[80:81], v[80:81], v[176:177] op_sel_hi:[1,0]
	v_pk_mul_f32 v[72:73], v[72:73], v[176:177] op_sel_hi:[1,0]
	v_mul_f32_e32 v80, 0xbfb8aa3b, v80
	v_add_f32_e32 v86, 1.0, v86
	v_mul_f32_e32 v81, 0xbfb8aa3b, v81
	v_exp_f32_e32 v80, v80
	v_exp_f32_e32 v81, v81
	v_pk_mul_f32 v[70:71], v[70:71], v[176:177] op_sel_hi:[1,0]
	v_pk_mul_f32 v[58:59], v[58:59], v[174:175] op_sel_hi:[1,0]
	v_add_f32_e32 v80, 1.0, v80
	v_add_f32_e32 v81, 1.0, v81
	v_rcp_f32_e32 v80, v80
	v_rcp_f32_e32 v81, v81
	v_mul_f32_e32 v70, 0xbfb8aa3b, v70
	v_exp_f32_e32 v70, v70
	v_mul_f32_e32 v58, 0xbfb8aa3b, v58
	v_exp_f32_e32 v58, v58
	v_pk_mul_f32 v[62:63], v[62:63], v[174:175] op_sel_hi:[1,0]
	v_add_f32_e32 v70, 1.0, v70
	v_mul_f32_e32 v62, 0xbfb8aa3b, v62
	v_exp_f32_e32 v62, v62
	v_add_f32_e32 v58, 1.0, v58
	v_pk_mul_f32 v[60:61], v[60:61], v[174:175] op_sel_hi:[1,0]
	v_pk_mul_f32 v[64:65], v[64:65], v[174:175] op_sel_hi:[1,0]
	v_add_f32_e32 v62, 1.0, v62
	v_pk_mul_f32 v[56:57], v[56:57], v[174:175] op_sel_hi:[1,0]
	v_pk_mul_f32 v[54:55], v[54:55], v[174:175] op_sel_hi:[1,0]
	v_pk_mul_f32 v[48:49], v[48:49], v[170:171] op_sel_hi:[1,0]
	v_mul_f32_e32 v54, 0xbfb8aa3b, v54
	v_exp_f32_e32 v54, v54
	v_pk_mul_f32 v[40:41], v[40:41], v[170:171] op_sel_hi:[1,0]
	v_pk_mul_f32 v[38:39], v[38:39], v[170:171] op_sel_hi:[1,0]
	v_pk_mul_f32 v[16:17], v[16:17], v[0:1] op_sel_hi:[1,0]
	v_add_f32_e32 v54, 1.0, v54
	v_mul_f32_e32 v38, 0xbfb8aa3b, v38
	v_exp_f32_e32 v38, v38
	v_pk_mul_f32 v[14:15], v[14:15], v[0:1] op_sel_hi:[1,0]
	v_pk_mul_f32 v[6:7], v[6:7], v[0:1] op_sel_hi:[1,0]
	v_cmp_gt_u32_e32 vcc, 16, v214
	v_add_f32_e32 v38, 1.0, v38
	s_waitcnt vmcnt(0)
	v_lshlrev_b32_e32 v200, 16, v122
	v_and_b32_e32 v201, 0xffff0000, v122
	v_mul_f32_e32 v122, 0xbfb8aa3b, v128
	v_exp_f32_e32 v122, v122
	v_lshlrev_b32_e32 v206, 16, v123
	v_and_b32_e32 v207, 0xffff0000, v123
	v_lshlrev_b32_e32 v208, 16, v124
	v_add_f32_e32 v122, 1.0, v122
	v_rcp_f32_e32 v202, v122
	v_mul_f32_e32 v122, 0xbfb8aa3b, v129
	v_exp_f32_e32 v122, v122
	v_and_b32_e32 v209, 0xffff0000, v124
	v_lshlrev_b32_e32 v212, 16, v125
	v_and_b32_e32 v213, 0xffff0000, v125
	v_add_f32_e32 v122, 1.0, v122
	v_rcp_f32_e32 v203, v122
	v_mul_f32_e32 v122, 0xbfb8aa3b, v204
	v_exp_f32_e32 v122, v122
	s_nop 0
	v_add_f32_e32 v122, 1.0, v122
	v_rcp_f32_e32 v204, v122
	v_mul_f32_e32 v122, 0xbfb8aa3b, v205
	v_exp_f32_e32 v122, v122
	s_nop 0
	v_add_f32_e32 v122, 1.0, v122
	v_rcp_f32_e32 v205, v122
	v_mul_f32_e32 v122, 0xbfb8aa3b, v210
	v_exp_f32_e32 v122, v122
	s_nop 0
	v_add_f32_e32 v122, 1.0, v122
	v_rcp_f32_e32 v210, v122
	v_mul_f32_e32 v122, 0xbfb8aa3b, v211
	v_exp_f32_e32 v122, v122
	s_nop 0
	v_add_f32_e32 v122, 1.0, v122
	v_rcp_f32_e32 v211, v122
	v_lshlrev_b64 v[122:123], 12, v[164:165]
	v_lshl_add_u64 v[122:123], s[6:7], 0, v[122:123]
	v_lshlrev_b64 v[164:165], 2, v[196:197]
	v_lshl_add_u64 v[196:197], v[122:123], 0, v[164:165]
	global_load_dwordx4 v[224:227], v217, s[12:13] offset:256
	global_load_dwordx4 v[122:125], v[196:197], off offset:16
	global_load_dwordx4 v[126:129], v[196:197], off
	s_waitcnt vmcnt(0)
; __device__ __forceinline__ unsigned cvtpk(float lo, float hi) { f32x2 v = {lo, hi}; bf16x2_t b = __builtin_convertvector(v, bf16x2_t); return __builtin_bit_cast(unsigned, b); }
; __device__ __forceinline__ float sigmoidf_(float v) { return __builtin_amdgcn_rcpf(1.0f + __expf(-v)); }
; #define EPI_LOOP_ROWS for (int ai = 0; ai < 2; ++ai) _Pragma("unroll") for (int m = 0; m < 4; ++m)
;     __device__ __forceinline__ void operator()(const f32x4 (&acc)[2][2][4][2], const Unit& u, int wv) const {
;     ...
;         EPI_LOOP_ROWS { const size_t row = (size_t)(row0 + ai * HALF + m * 16);
;             const float rstd = rs[ai][m]; float ssq = 0.f;
; #pragma unroll
;             for (int bj = 0; bj < 2; ++bj) { const int col = col0 + bj * HALF;
;                 f32x4 v0 = acc[ai][bj][m][0] * rstd, v1 = acc[ai][bj][m][1] * rstd;
;                 if (PP) { const u32x4 g = *(const u32x4*)(PP + row * 1024 + col);
;                     v0[0] = sigmoidf_(v0[0]) * __builtin_bit_cast(float, g.x << 16); v0[1] = sigmoidf_(v0[1]) * __builtin_bit_cast(float, g.x & 0xffff0000u);
;                     v0[2] = sigmoidf_(v0[2]) * __builtin_bit_cast(float, g.y << 16); v0[3] = sigmoidf_(v0[3]) * __builtin_bit_cast(float, g.y & 0xffff0000u);
;                     v1[0] = sigmoidf_(v1[0]) * __builtin_bit_cast(float, g.z << 16); v1[1] = sigmoidf_(v1[1]) * __builtin_bit_cast(float, g.z & 0xffff0000u);
;                     v1[2] = sigmoidf_(v1[2]) * __builtin_bit_cast(float, g.w << 16); v1[3] = sigmoidf_(v1[3]) * __builtin_bit_cast(float, g.w & 0xffff0000u); }
;                 float* xp = X + row * 1024 + col;
;                 v0 += *(const f32x4*)xp; v1 += *(const f32x4*)(xp + 4);
;                 *(f32x4*)xp = v0; *(f32x4*)(xp + 4) = v1;
;                 u32x4 w; w.x = cvtpk(v0[0], v0[1]); w.y = cvtpk(v0[2], v0[3]); w.z = cvtpk(v1[0], v1[1]); w.w = cvtpk(v1[2], v1[3]);
;                 *(u32x4*)(XB + row * 1024 + col) = w;
;                 ssq += ((v0[0] * v0[0] + v0[1] * v0[1]) + (v0[2] * v0[2] + v0[3] * v0[3])) + ((v1[0] * v1[0] + v1[1] * v1[1]) + (v1[2] * v1[2] + v1[3] * v1[3])); }
;             sq[ai][m] = ssq;
;             if (m & 1) asm volatile("" ::: "memory"); }
	v_pk_fma_f32 v[128:129], v[202:203], v[206:207], v[128:129]
	v_pk_fma_f32 v[126:127], v[198:199], v[200:201], v[126:127]
	v_pk_fma_f32 v[200:201], v[210:211], v[212:213], v[124:125]
	v_mul_f32_e32 v124, v127, v127
	v_mul_f32_e32 v125, v129, v129
	v_pk_fma_f32 v[198:199], v[204:205], v[208:209], v[122:123]
	v_fmac_f32_e32 v124, v126, v126
	v_fmac_f32_e32 v125, v128, v128
	global_store_dwordx4 v[196:197], v[126:129], off
	global_store_dwordx4 v[196:197], v[198:201], off offset:16
	v_cvt_pk_bf16_f32 v202, v126, v127
	v_add_f32_e32 v124, v124, v125
	v_mul_f32_e32 v125, v199, v199
	v_mul_f32_e32 v126, v201, v201
	v_fmac_f32_e32 v125, v198, v198
	v_fmac_f32_e32 v126, v200, v200
	v_add_f32_e32 v125, v125, v126
	v_add_f32_e32 v167, v124, v125
	v_pk_mul_f32 v[124:125], v[116:117], v[188:189] op_sel_hi:[1,0]
	v_pk_mul_f32 v[126:127], v[114:115], v[188:189] op_sel_hi:[1,0]
	v_mov_b32_e32 v114, v224
	v_mov_b32_e32 v115, v225
	v_mov_b32_e32 v116, v226
	v_mov_b32_e32 v117, v227
	v_lshl_add_u64 v[122:123], s[66:67], 0, v[192:193]
	v_cvt_pk_bf16_f32 v203, v128, v129
	v_rcp_f32_e32 v128, v118
	v_mul_f32_e32 v118, 0xbfb8aa3b, v119
	v_exp_f32_e32 v118, v118
	v_cvt_pk_bf16_f32 v204, v198, v199
	v_cvt_pk_bf16_f32 v205, v200, v201
	v_lshl_add_u64 v[122:123], v[122:123], 0, v[160:161]
	global_store_dwordx4 v[122:123], v[202:205], off
	v_add_f32_e32 v118, 1.0, v118
	v_rcp_f32_e32 v129, v118
	v_pk_mul_f32 v[32:33], v[32:33], v[166:167] op_sel_hi:[1,0]
	v_pk_mul_f32 v[24:25], v[24:25], v[166:167] op_sel_hi:[1,0]
	v_pk_mul_f32 v[22:23], v[22:23], v[166:167] op_sel_hi:[1,0]
	s_waitcnt vmcnt(1)
	v_lshlrev_b32_e32 v190, 16, v114
	v_and_b32_e32 v191, 0xffff0000, v114
	v_mul_f32_e32 v114, 0xbfb8aa3b, v120
	v_exp_f32_e32 v114, v114
	v_lshlrev_b32_e32 v198, 16, v115
	v_and_b32_e32 v199, 0xffff0000, v115
	v_lshlrev_b32_e32 v200, 16, v116
	v_add_f32_e32 v114, 1.0, v114
	v_rcp_f32_e32 v192, v114
	v_mul_f32_e32 v114, 0xbfb8aa3b, v121
	v_exp_f32_e32 v114, v114
	v_and_b32_e32 v201, 0xffff0000, v116
	v_lshlrev_b32_e32 v202, 16, v117
	v_and_b32_e32 v203, 0xffff0000, v117
	v_add_f32_e32 v114, 1.0, v114
	v_rcp_f32_e32 v193, v114
	v_mul_f32_e32 v114, 0xbfb8aa3b, v126
	v_exp_f32_e32 v114, v114
	v_mul_f32_e32 v22, 0xbfb8aa3b, v22
	v_exp_f32_e32 v22, v22
	v_add_f32_e32 v114, 1.0, v114
	v_rcp_f32_e32 v126, v114
	v_mul_f32_e32 v114, 0xbfb8aa3b, v127
	v_exp_f32_e32 v114, v114
	v_add_f32_e32 v22, 1.0, v22
	v_add_f32_e32 v114, 1.0, v114
	v_rcp_f32_e32 v127, v114
	v_mul_f32_e32 v114, 0xbfb8aa3b, v124
	v_exp_f32_e32 v114, v114
	s_nop 0
	v_add_f32_e32 v114, 1.0, v114
	v_rcp_f32_e32 v124, v114
	v_mul_f32_e32 v114, 0xbfb8aa3b, v125
	v_exp_f32_e32 v114, v114
	s_nop 0
	v_add_f32_e32 v114, 1.0, v114
	v_rcp_f32_e32 v125, v114
	v_add_u32_e32 v218, 0x8000, v217
	global_load_dwordx4 v[220:223], v218, s[12:13]
	global_load_dwordx4 v[114:117], v[196:197], off offset:528
	global_load_dwordx4 v[118:121], v[196:197], off offset:512
	s_waitcnt vmcnt(1)
	v_pk_fma_f32 v[114:115], v[126:127], v[200:201], v[114:115]
	s_waitcnt vmcnt(0)
	v_pk_fma_f32 v[120:121], v[192:193], v[198:199], v[120:121]
	v_pk_fma_f32 v[118:119], v[128:129], v[190:191], v[118:119]
	v_pk_fma_f32 v[116:117], v[124:125], v[202:203], v[116:117]
	global_store_dwordx4 v[196:197], v[118:121], off offset:512
	global_store_dwordx4 v[196:197], v[114:117], off offset:528
	v_cvt_pk_bf16_f32 v124, v118, v119
	v_cvt_pk_bf16_f32 v126, v114, v115
	v_mul_f32_e32 v119, v119, v119
	v_mul_f32_e32 v115, v115, v115
	v_fmac_f32_e32 v119, v118, v118
	v_mul_f32_e32 v118, v121, v121
	v_fmac_f32_e32 v115, v114, v114
	v_mul_f32_e32 v114, v117, v117
	v_fmac_f32_e32 v118, v120, v120
	v_fmac_f32_e32 v114, v116, v116
	v_add_f32_e32 v118, v119, v118
	v_add_f32_e32 v114, v115, v114
	v_add_f32_e32 v114, v118, v114
	v_add_f32_e32 v128, v167, v114
	v_lshlrev_b64 v[114:115], 11, v[186:187]
	v_cvt_pk_bf16_f32 v127, v116, v117
	v_pk_mul_f32 v[116:117], v[106:107], v[184:185] op_sel_hi:[1,0]
	v_lshl_add_u64 v[106:107], s[12:13], 0, v[114:115]
	v_cvt_pk_bf16_f32 v125, v120, v121
	v_lshl_add_u64 v[106:107], v[106:107], 0, v[160:161]
	global_store_dwordx4 v[122:123], v[124:127], off offset:256
	v_mov_b32_e32 v122, v220
	v_mov_b32_e32 v123, v221
	v_mov_b32_e32 v124, v222
	v_mov_b32_e32 v125, v223
	v_mul_f32_e32 v116, 0xbfb8aa3b, v116
	v_pk_mul_f32 v[126:127], v[108:109], v[184:185] op_sel_hi:[1,0]
	v_mul_f32_e32 v108, 0xbfb8aa3b, v110
	v_mul_f32_e32 v109, 0xbfb8aa3b, v111
	v_exp_f32_e32 v108, v108
	v_exp_f32_e32 v109, v109
	v_mul_f32_e32 v117, 0xbfb8aa3b, v117
	v_exp_f32_e32 v116, v116
	v_exp_f32_e32 v117, v117
	v_add_f32_e32 v108, 1.0, v108
	v_add_f32_e32 v109, 1.0, v109
	v_rcp_f32_e32 v108, v108
	v_rcp_f32_e32 v109, v109
	v_add_f32_e32 v116, 1.0, v116
	v_add_f32_e32 v117, 1.0, v117
	v_rcp_f32_e32 v116, v116
	v_rcp_f32_e32 v117, v117
	s_waitcnt vmcnt(0)
	v_lshlrev_b32_e32 v110, 16, v122
	v_and_b32_e32 v111, 0xffff0000, v122
	v_lshlrev_b32_e32 v118, 16, v123
	v_and_b32_e32 v119, 0xffff0000, v123
	v_mul_f32_e32 v122, 0xbfb8aa3b, v126
	v_mul_f32_e32 v123, 0xbfb8aa3b, v127
	v_lshlrev_b64 v[126:127], 12, v[186:187]
	v_lshl_add_u64 v[126:127], s[6:7], 0, v[126:127]
	v_lshl_add_u64 v[126:127], v[126:127], 0, v[164:165]
	v_add_u32_e32 v218, 0x8000, v217
	global_load_dwordx4 v[224:227], v218, s[12:13] offset:256
	global_load_dwordx4 v[190:193], v[126:127], off offset:16
	global_load_dwordx4 v[196:199], v[126:127], off
	v_exp_f32_e32 v122, v122
	v_exp_f32_e32 v123, v123
	v_lshlrev_b32_e32 v120, 16, v124
	v_and_b32_e32 v121, 0xffff0000, v124
	v_add_f32_e32 v122, 1.0, v122
	v_add_f32_e32 v123, 1.0, v123
	v_rcp_f32_e32 v122, v122
	v_rcp_f32_e32 v123, v123
	v_lshlrev_b32_e32 v124, 16, v125
	v_and_b32_e32 v125, 0xffff0000, v125
	s_waitcnt vmcnt(1)
; __device__ __forceinline__ unsigned cvtpk(float lo, float hi) { f32x2 v = {lo, hi}; bf16x2_t b = __builtin_convertvector(v, bf16x2_t); return __builtin_bit_cast(unsigned, b); }
; __device__ __forceinline__ float sigmoidf_(float v) { return __builtin_amdgcn_rcpf(1.0f + __expf(-v)); }
; #define EPI_LOOP_ROWS for (int ai = 0; ai < 2; ++ai) _Pragma("unroll") for (int m = 0; m < 4; ++m)
;     __device__ __forceinline__ void operator()(const f32x4 (&acc)[2][2][4][2], const Unit& u, int wv) const {
;     ...
;         EPI_LOOP_ROWS { const size_t row = (size_t)(row0 + ai * HALF + m * 16);
;             const float rstd = rs[ai][m]; float ssq = 0.f;
; #pragma unroll
;             for (int bj = 0; bj < 2; ++bj) { const int col = col0 + bj * HALF;
;                 f32x4 v0 = acc[ai][bj][m][0] * rstd, v1 = acc[ai][bj][m][1] * rstd;
;                 if (PP) { const u32x4 g = *(const u32x4*)(PP + row * 1024 + col);
;                     v0[0] = sigmoidf_(v0[0]) * __builtin_bit_cast(float, g.x << 16); v0[1] = sigmoidf_(v0[1]) * __builtin_bit_cast(float, g.x & 0xffff0000u);
;                     v0[2] = sigmoidf_(v0[2]) * __builtin_bit_cast(float, g.y << 16); v0[3] = sigmoidf_(v0[3]) * __builtin_bit_cast(float, g.y & 0xffff0000u);
;                     v1[0] = sigmoidf_(v1[0]) * __builtin_bit_cast(float, g.z << 16); v1[1] = sigmoidf_(v1[1]) * __builtin_bit_cast(float, g.z & 0xffff0000u);
;                     v1[2] = sigmoidf_(v1[2]) * __builtin_bit_cast(float, g.w << 16); v1[3] = sigmoidf_(v1[3]) * __builtin_bit_cast(float, g.w & 0xffff0000u); }
;                 float* xp = X + row * 1024 + col;
;                 v0 += *(const f32x4*)xp; v1 += *(const f32x4*)(xp + 4);
;                 *(f32x4*)xp = v0; *(f32x4*)(xp + 4) = v1;
;                 u32x4 w; w.x = cvtpk(v0[0], v0[1]); w.y = cvtpk(v0[2], v0[3]); w.z = cvtpk(v1[0], v1[1]); w.w = cvtpk(v1[2], v1[3]);
;                 *(u32x4*)(XB + row * 1024 + col) = w;
;                 ssq += ((v0[0] * v0[0] + v0[1] * v0[1]) + (v0[2] * v0[2] + v0[3] * v0[3])) + ((v1[0] * v1[0] + v1[1] * v1[1]) + (v1[2] * v1[2] + v1[3] * v1[3])); }
;             sq[ai][m] = ssq;
;             if (m & 1) asm volatile("" ::: "memory"); }
	v_pk_fma_f32 v[116:117], v[116:117], v[120:121], v[190:191]
	s_waitcnt vmcnt(0)
	v_pk_fma_f32 v[112:113], v[112:113], v[118:119], v[198:199]
	v_pk_fma_f32 v[110:111], v[108:109], v[110:111], v[196:197]
	v_pk_fma_f32 v[118:119], v[122:123], v[124:125], v[192:193]
	global_store_dwordx4 v[126:127], v[110:113], off
	global_store_dwordx4 v[126:127], v[116:119], off offset:16
	v_cvt_pk_bf16_f32 v120, v110, v111
	v_mul_f32_e32 v111, v111, v111
	v_fmac_f32_e32 v111, v110, v110
	v_mul_f32_e32 v110, v113, v113
	v_fmac_f32_e32 v110, v112, v112
	v_cvt_pk_bf16_f32 v121, v112, v113
	v_add_f32_e32 v110, v111, v110
	v_mul_f32_e32 v111, v117, v117
	v_mul_f32_e32 v112, v119, v119
	v_fmac_f32_e32 v111, v116, v116
	v_fmac_f32_e32 v112, v118, v118
	v_add_f32_e32 v111, v111, v112
	v_add_f32_e32 v124, v110, v111
	v_pk_mul_f32 v[110:111], v[100:101], v[184:185] op_sel_hi:[1,0]
	v_pk_mul_f32 v[112:113], v[98:99], v[184:185] op_sel_hi:[1,0]
	v_mov_b32_e32 v98, v224
	v_mov_b32_e32 v99, v225
	v_mov_b32_e32 v100, v226
	v_mov_b32_e32 v101, v227
	v_lshl_add_u64 v[108:109], s[66:67], 0, v[114:115]
	v_cvt_pk_bf16_f32 v122, v116, v117
	v_rcp_f32_e32 v106, v102
	v_mul_f32_e32 v102, 0xbfb8aa3b, v103
	v_exp_f32_e32 v102, v102
	v_cvt_pk_bf16_f32 v123, v118, v119
	v_lshl_add_u64 v[108:109], v[108:109], 0, v[160:161]
	global_store_dwordx4 v[108:109], v[120:123], off
	v_add_f32_e32 v102, 1.0, v102
	v_rcp_f32_e32 v107, v102
	s_waitcnt vmcnt(1)
	v_lshlrev_b32_e32 v114, 16, v98
	v_and_b32_e32 v115, 0xffff0000, v98
	v_mul_f32_e32 v98, 0xbfb8aa3b, v104
	v_exp_f32_e32 v98, v98
	v_lshlrev_b32_e32 v118, 16, v99
	v_and_b32_e32 v119, 0xffff0000, v99
	v_lshlrev_b32_e32 v120, 16, v100
	v_add_f32_e32 v98, 1.0, v98
	v_rcp_f32_e32 v116, v98
	v_mul_f32_e32 v98, 0xbfb8aa3b, v105
	v_exp_f32_e32 v98, v98
	v_and_b32_e32 v121, 0xffff0000, v100
	v_lshlrev_b32_e32 v122, 16, v101
	v_and_b32_e32 v123, 0xffff0000, v101
	v_add_f32_e32 v98, 1.0, v98
	v_rcp_f32_e32 v117, v98
	v_mul_f32_e32 v98, 0xbfb8aa3b, v112
	v_exp_f32_e32 v98, v98
	s_nop 0
	v_add_f32_e32 v98, 1.0, v98
	v_rcp_f32_e32 v112, v98
	v_mul_f32_e32 v98, 0xbfb8aa3b, v113
	v_exp_f32_e32 v98, v98
	s_nop 0
	v_add_f32_e32 v98, 1.0, v98
	v_rcp_f32_e32 v113, v98
	v_mul_f32_e32 v98, 0xbfb8aa3b, v110
	v_exp_f32_e32 v98, v98
	s_nop 0
	v_add_f32_e32 v98, 1.0, v98
	v_rcp_f32_e32 v110, v98
	v_mul_f32_e32 v98, 0xbfb8aa3b, v111
	v_exp_f32_e32 v98, v98
	s_nop 0
	v_add_f32_e32 v98, 1.0, v98
	v_rcp_f32_e32 v111, v98
	v_add_u32_e32 v218, 0x10000, v217
	global_load_dwordx4 v[220:223], v218, s[12:13]
	global_load_dwordx4 v[98:101], v[126:127], off offset:528
	global_load_dwordx4 v[102:105], v[126:127], off offset:512
	s_waitcnt vmcnt(1)
	v_pk_fma_f32 v[98:99], v[112:113], v[120:121], v[98:99]
	s_waitcnt vmcnt(0)
	v_pk_fma_f32 v[104:105], v[116:117], v[118:119], v[104:105]
	v_pk_fma_f32 v[102:103], v[106:107], v[114:115], v[102:103]
	v_pk_fma_f32 v[100:101], v[110:111], v[122:123], v[100:101]
	global_store_dwordx4 v[126:127], v[102:105], off offset:512
	global_store_dwordx4 v[126:127], v[98:101], off offset:528
	v_cvt_pk_bf16_f32 v110, v102, v103
	v_cvt_pk_bf16_f32 v112, v98, v99
	v_mul_f32_e32 v103, v103, v103
	v_mul_f32_e32 v99, v99, v99
	v_fmac_f32_e32 v103, v102, v102
	v_mul_f32_e32 v102, v105, v105
	v_fmac_f32_e32 v99, v98, v98
	v_mul_f32_e32 v98, v101, v101
	v_fmac_f32_e32 v102, v104, v104
	v_fmac_f32_e32 v98, v100, v100
	v_add_f32_e32 v102, v103, v102
	v_add_f32_e32 v98, v99, v98
	v_cvt_pk_bf16_f32 v111, v104, v105
	v_cvt_pk_bf16_f32 v113, v100, v101
	v_add_f32_e32 v98, v102, v98
	v_lshlrev_b64 v[100:101], 11, v[180:181]
	global_store_dwordx4 v[108:109], v[110:113], off offset:256
	v_add_f32_e32 v120, v124, v98
	v_lshl_add_u64 v[98:99], s[12:13], 0, v[100:101]
	v_lshl_add_u64 v[98:99], v[98:99], 0, v[160:161]
	v_mov_b32_e32 v116, v220
	v_mov_b32_e32 v117, v221
	v_mov_b32_e32 v118, v222
	v_mov_b32_e32 v119, v223
	v_rcp_f32_e32 v110, v90
	v_mul_f32_e32 v90, 0xbfb8aa3b, v91
	v_exp_f32_e32 v90, v90
	v_rcp_f32_e32 v104, v94
	v_mul_f32_e32 v94, 0xbfb8aa3b, v95
	v_exp_f32_e32 v94, v94
	v_add_f32_e32 v90, 1.0, v90
	v_rcp_f32_e32 v111, v90
	v_mul_f32_e32 v90, 0xbfb8aa3b, v92
	v_exp_f32_e32 v90, v90
	v_add_f32_e32 v94, 1.0, v94
	v_rcp_f32_e32 v105, v94
	v_mul_f32_e32 v94, 0xbfb8aa3b, v96
	v_exp_f32_e32 v94, v94
	v_add_f32_e32 v90, 1.0, v90
	v_add_f32_e32 v94, 1.0, v94
	v_rcp_f32_e32 v108, v94
	v_mul_f32_e32 v94, 0xbfb8aa3b, v97
	v_exp_f32_e32 v94, v94
	s_waitcnt vmcnt(0)
	v_lshlrev_b32_e32 v106, 16, v116
	v_and_b32_e32 v107, 0xffff0000, v116
	v_rcp_f32_e32 v116, v90
	v_mul_f32_e32 v90, 0xbfb8aa3b, v93
	v_exp_f32_e32 v90, v90
	v_lshlrev_b32_e32 v112, 16, v117
	v_and_b32_e32 v113, 0xffff0000, v117
	v_add_f32_e32 v94, 1.0, v94
	v_add_f32_e32 v90, 1.0, v90
	v_rcp_f32_e32 v117, v90
	v_lshlrev_b64 v[90:91], 12, v[180:181]
	v_lshl_add_u64 v[90:91], s[6:7], 0, v[90:91]
	v_lshl_add_u64 v[102:103], v[90:91], 0, v[164:165]
	v_rcp_f32_e32 v109, v94
	v_add_u32_e32 v218, 0x10000, v217
	global_load_dwordx4 v[224:227], v218, s[12:13] offset:256
	global_load_dwordx4 v[90:93], v[102:103], off offset:16
	global_load_dwordx4 v[94:97], v[102:103], off
	v_lshlrev_b32_e32 v114, 16, v118
	v_and_b32_e32 v115, 0xffff0000, v118
	v_lshlrev_b32_e32 v118, 16, v119
	v_and_b32_e32 v119, 0xffff0000, v119
	s_waitcnt vmcnt(0)
; __device__ __forceinline__ unsigned cvtpk(float lo, float hi) { f32x2 v = {lo, hi}; bf16x2_t b = __builtin_convertvector(v, bf16x2_t); return __builtin_bit_cast(unsigned, b); }
; __device__ __forceinline__ float sigmoidf_(float v) { return __builtin_amdgcn_rcpf(1.0f + __expf(-v)); }
; #define EPI_LOOP_ROWS for (int ai = 0; ai < 2; ++ai) _Pragma("unroll") for (int m = 0; m < 4; ++m)
;     __device__ __forceinline__ void operator()(const f32x4 (&acc)[2][2][4][2], const Unit& u, int wv) const {
;     ...
;         EPI_LOOP_ROWS { const size_t row = (size_t)(row0 + ai * HALF + m * 16);
;             const float rstd = rs[ai][m]; float ssq = 0.f;
; #pragma unroll
;             for (int bj = 0; bj < 2; ++bj) { const int col = col0 + bj * HALF;
;                 f32x4 v0 = acc[ai][bj][m][0] * rstd, v1 = acc[ai][bj][m][1] * rstd;
;                 if (PP) { const u32x4 g = *(const u32x4*)(PP + row * 1024 + col);
;                     v0[0] = sigmoidf_(v0[0]) * __builtin_bit_cast(float, g.x << 16); v0[1] = sigmoidf_(v0[1]) * __builtin_bit_cast(float, g.x & 0xffff0000u);
;                     v0[2] = sigmoidf_(v0[2]) * __builtin_bit_cast(float, g.y << 16); v0[3] = sigmoidf_(v0[3]) * __builtin_bit_cast(float, g.y & 0xffff0000u);
;                     v1[0] = sigmoidf_(v1[0]) * __builtin_bit_cast(float, g.z << 16); v1[1] = sigmoidf_(v1[1]) * __builtin_bit_cast(float, g.z & 0xffff0000u);
;                     v1[2] = sigmoidf_(v1[2]) * __builtin_bit_cast(float, g.w << 16); v1[3] = sigmoidf_(v1[3]) * __builtin_bit_cast(float, g.w & 0xffff0000u); }
;                 float* xp = X + row * 1024 + col;
;                 v0 += *(const f32x4*)xp; v1 += *(const f32x4*)(xp + 4);
;                 *(f32x4*)xp = v0; *(f32x4*)(xp + 4) = v1;
;                 u32x4 w; w.x = cvtpk(v0[0], v0[1]); w.y = cvtpk(v0[2], v0[3]); w.z = cvtpk(v1[0], v1[1]); w.w = cvtpk(v1[2], v1[3]);
;                 *(u32x4*)(XB + row * 1024 + col) = w;
;                 ssq += ((v0[0] * v0[0] + v0[1] * v0[1]) + (v0[2] * v0[2] + v0[3] * v0[3])) + ((v1[0] * v1[0] + v1[1] * v1[1]) + (v1[2] * v1[2] + v1[3] * v1[3])); }
;             sq[ai][m] = ssq;
;             if (m & 1) asm volatile("" ::: "memory"); }
	v_pk_fma_f32 v[96:97], v[108:109], v[112:113], v[96:97]
	v_pk_fma_f32 v[94:95], v[104:105], v[106:107], v[94:95]
	v_pk_fma_f32 v[106:107], v[116:117], v[118:119], v[92:93]
	v_mul_f32_e32 v92, v95, v95
	v_mul_f32_e32 v93, v97, v97
	v_pk_fma_f32 v[104:105], v[110:111], v[114:115], v[90:91]
	v_fmac_f32_e32 v92, v94, v94
	v_fmac_f32_e32 v93, v96, v96
	global_store_dwordx4 v[102:103], v[94:97], off
	global_store_dwordx4 v[102:103], v[104:107], off offset:16
	v_cvt_pk_bf16_f32 v108, v94, v95
	v_add_f32_e32 v92, v92, v93
	v_mul_f32_e32 v93, v105, v105
	v_mul_f32_e32 v94, v107, v107
	v_lshl_add_u64 v[90:91], s[66:67], 0, v[100:101]
	v_fmac_f32_e32 v93, v104, v104
	v_fmac_f32_e32 v94, v106, v106
	v_cvt_pk_bf16_f32 v109, v96, v97
	v_cvt_pk_bf16_f32 v110, v104, v105
	v_cvt_pk_bf16_f32 v111, v106, v107
	v_lshl_add_u64 v[90:91], v[90:91], 0, v[160:161]
	v_add_f32_e32 v93, v93, v94
	global_store_dwordx4 v[90:91], v[108:111], off
	v_pk_mul_f32 v[94:95], v[82:83], v[182:183] op_sel_hi:[1,0]
	v_rcp_f32_e32 v96, v86
	v_add_f32_e32 v110, v92, v93
	v_pk_mul_f32 v[92:93], v[84:85], v[182:183] op_sel_hi:[1,0]
	v_mov_b32_e32 v82, v224
	v_mov_b32_e32 v83, v225
	v_mov_b32_e32 v84, v226
	v_mov_b32_e32 v85, v227
	v_mul_f32_e32 v86, 0xbfb8aa3b, v87
	v_exp_f32_e32 v86, v86
	s_waitcnt vmcnt(0)
	v_lshlrev_b32_e32 v98, 16, v82
	v_and_b32_e32 v99, 0xffff0000, v82
	v_mul_f32_e32 v82, 0xbfb8aa3b, v88
	v_exp_f32_e32 v82, v82
	v_add_f32_e32 v86, 1.0, v86
	v_rcp_f32_e32 v97, v86
	v_lshlrev_b32_e32 v104, 16, v83
	v_add_f32_e32 v82, 1.0, v82
	v_rcp_f32_e32 v100, v82
	v_mul_f32_e32 v82, 0xbfb8aa3b, v89
	v_exp_f32_e32 v82, v82
	v_and_b32_e32 v105, 0xffff0000, v83
	v_lshlrev_b32_e32 v106, 16, v84
	v_and_b32_e32 v107, 0xffff0000, v84
	v_add_f32_e32 v82, 1.0, v82
	v_rcp_f32_e32 v101, v82
	v_mul_f32_e32 v82, 0xbfb8aa3b, v94
	v_exp_f32_e32 v82, v82
	v_lshlrev_b32_e32 v108, 16, v85
	v_and_b32_e32 v109, 0xffff0000, v85
	v_add_f32_e32 v82, 1.0, v82
	v_rcp_f32_e32 v94, v82
	v_mul_f32_e32 v82, 0xbfb8aa3b, v95
	v_exp_f32_e32 v82, v82
	s_nop 0
	v_add_f32_e32 v82, 1.0, v82
	v_rcp_f32_e32 v95, v82
	v_mul_f32_e32 v82, 0xbfb8aa3b, v92
	v_exp_f32_e32 v82, v82
	s_nop 0
	v_add_f32_e32 v82, 1.0, v82
	v_rcp_f32_e32 v92, v82
	v_mul_f32_e32 v82, 0xbfb8aa3b, v93
	v_exp_f32_e32 v82, v82
	s_nop 0
	v_add_f32_e32 v82, 1.0, v82
	v_rcp_f32_e32 v93, v82
	v_add_u32_e32 v218, 0x18000, v217
	global_load_dwordx4 v[220:223], v218, s[12:13]
	global_load_dwordx4 v[82:85], v[102:103], off offset:528
	global_load_dwordx4 v[86:89], v[102:103], off offset:512
	s_waitcnt vmcnt(1)
	v_pk_fma_f32 v[82:83], v[94:95], v[106:107], v[82:83]
	s_waitcnt vmcnt(0)
	v_pk_fma_f32 v[88:89], v[100:101], v[104:105], v[88:89]
	v_pk_fma_f32 v[86:87], v[96:97], v[98:99], v[86:87]
	v_pk_fma_f32 v[84:85], v[92:93], v[108:109], v[84:85]
	global_store_dwordx4 v[102:103], v[86:89], off offset:512
	global_store_dwordx4 v[102:103], v[82:85], off offset:528
	v_cvt_pk_bf16_f32 v92, v86, v87
	v_cvt_pk_bf16_f32 v94, v82, v83
	v_mul_f32_e32 v87, v87, v87
	v_mul_f32_e32 v83, v83, v83
	v_fmac_f32_e32 v87, v86, v86
	v_mul_f32_e32 v86, v89, v89
	v_fmac_f32_e32 v83, v82, v82
	v_mul_f32_e32 v82, v85, v85
	v_fmac_f32_e32 v86, v88, v88
	v_fmac_f32_e32 v82, v84, v84
	v_add_f32_e32 v86, v87, v86
	v_add_f32_e32 v82, v83, v82
	v_add_f32_e32 v82, v86, v82
	v_add_f32_e32 v96, v110, v82
	v_lshlrev_b64 v[82:83], 11, v[178:179]
	v_cvt_pk_bf16_f32 v95, v84, v85
	v_pk_mul_f32 v[84:85], v[74:75], v[176:177] op_sel_hi:[1,0]
	v_lshl_add_u64 v[74:75], s[12:13], 0, v[82:83]
	v_cvt_pk_bf16_f32 v93, v88, v89
	v_lshl_add_u64 v[74:75], v[74:75], 0, v[160:161]
	global_store_dwordx4 v[90:91], v[92:95], off offset:256
	v_mov_b32_e32 v90, v220
	v_mov_b32_e32 v91, v221
	v_mov_b32_e32 v92, v222
	v_mov_b32_e32 v93, v223
	v_mul_f32_e32 v84, 0xbfb8aa3b, v84
	v_pk_mul_f32 v[94:95], v[76:77], v[176:177] op_sel_hi:[1,0]
	v_mul_f32_e32 v76, 0xbfb8aa3b, v78
	v_mul_f32_e32 v77, 0xbfb8aa3b, v79
	v_exp_f32_e32 v76, v76
	v_exp_f32_e32 v77, v77
	v_mul_f32_e32 v85, 0xbfb8aa3b, v85
	v_exp_f32_e32 v84, v84
	v_exp_f32_e32 v85, v85
	v_add_f32_e32 v76, 1.0, v76
	v_add_f32_e32 v77, 1.0, v77
	v_rcp_f32_e32 v76, v76
	v_rcp_f32_e32 v77, v77
	v_add_f32_e32 v84, 1.0, v84
	v_add_f32_e32 v85, 1.0, v85
	v_rcp_f32_e32 v84, v84
	v_rcp_f32_e32 v85, v85
	s_waitcnt vmcnt(0)
	v_lshlrev_b32_e32 v78, 16, v90
	v_and_b32_e32 v79, 0xffff0000, v90
	v_lshlrev_b32_e32 v86, 16, v91
	v_and_b32_e32 v87, 0xffff0000, v91
	v_mul_f32_e32 v90, 0xbfb8aa3b, v94
	v_mul_f32_e32 v91, 0xbfb8aa3b, v95
	v_lshlrev_b64 v[94:95], 12, v[178:179]
	v_lshl_add_u64 v[94:95], s[6:7], 0, v[94:95]
	v_lshl_add_u64 v[94:95], v[94:95], 0, v[164:165]
	v_add_u32_e32 v218, 0x18000, v217
	global_load_dwordx4 v[224:227], v218, s[12:13] offset:256
	global_load_dwordx4 v[98:101], v[94:95], off offset:16
	global_load_dwordx4 v[102:105], v[94:95], off
	v_exp_f32_e32 v90, v90
	v_exp_f32_e32 v91, v91
	v_lshlrev_b32_e32 v88, 16, v92
	v_and_b32_e32 v89, 0xffff0000, v92
	v_add_f32_e32 v90, 1.0, v90
	v_add_f32_e32 v91, 1.0, v91
	v_rcp_f32_e32 v90, v90
	v_rcp_f32_e32 v91, v91
	v_lshlrev_b32_e32 v92, 16, v93
	v_and_b32_e32 v93, 0xffff0000, v93
	s_waitcnt vmcnt(1)
	v_pk_fma_f32 v[84:85], v[84:85], v[88:89], v[98:99]
	s_waitcnt vmcnt(0)
; __device__ __forceinline__ unsigned cvtpk(float lo, float hi) { f32x2 v = {lo, hi}; bf16x2_t b = __builtin_convertvector(v, bf16x2_t); return __builtin_bit_cast(unsigned, b); }
; __device__ __forceinline__ float sigmoidf_(float v) { return __builtin_amdgcn_rcpf(1.0f + __expf(-v)); }
; #define EPI_LOOP_ROWS for (int ai = 0; ai < 2; ++ai) _Pragma("unroll") for (int m = 0; m < 4; ++m)
;     __device__ __forceinline__ void operator()(const f32x4 (&acc)[2][2][4][2], const Unit& u, int wv) const {
;     ...
;         EPI_LOOP_ROWS { const size_t row = (size_t)(row0 + ai * HALF + m * 16);
;             const float rstd = rs[ai][m]; float ssq = 0.f;
; #pragma unroll
;             for (int bj = 0; bj < 2; ++bj) { const int col = col0 + bj * HALF;
;                 f32x4 v0 = acc[ai][bj][m][0] * rstd, v1 = acc[ai][bj][m][1] * rstd;
;                 if (PP) { const u32x4 g = *(const u32x4*)(PP + row * 1024 + col);
;                     v0[0] = sigmoidf_(v0[0]) * __builtin_bit_cast(float, g.x << 16); v0[1] = sigmoidf_(v0[1]) * __builtin_bit_cast(float, g.x & 0xffff0000u);
;                     v0[2] = sigmoidf_(v0[2]) * __builtin_bit_cast(float, g.y << 16); v0[3] = sigmoidf_(v0[3]) * __builtin_bit_cast(float, g.y & 0xffff0000u);
;                     v1[0] = sigmoidf_(v1[0]) * __builtin_bit_cast(float, g.z << 16); v1[1] = sigmoidf_(v1[1]) * __builtin_bit_cast(float, g.z & 0xffff0000u);
;                     v1[2] = sigmoidf_(v1[2]) * __builtin_bit_cast(float, g.w << 16); v1[3] = sigmoidf_(v1[3]) * __builtin_bit_cast(float, g.w & 0xffff0000u); }
;                 float* xp = X + row * 1024 + col;
;                 v0 += *(const f32x4*)xp; v1 += *(const f32x4*)(xp + 4);
;                 *(f32x4*)xp = v0; *(f32x4*)(xp + 4) = v1;
;                 u32x4 w; w.x = cvtpk(v0[0], v0[1]); w.y = cvtpk(v0[2], v0[3]); w.z = cvtpk(v1[0], v1[1]); w.w = cvtpk(v1[2], v1[3]);
;                 *(u32x4*)(XB + row * 1024 + col) = w;
;                 ssq += ((v0[0] * v0[0] + v0[1] * v0[1]) + (v0[2] * v0[2] + v0[3] * v0[3])) + ((v1[0] * v1[0] + v1[1] * v1[1]) + (v1[2] * v1[2] + v1[3] * v1[3])); }
;             sq[ai][m] = ssq;
;             if (m & 1) asm volatile("" ::: "memory"); }
	v_pk_fma_f32 v[80:81], v[80:81], v[86:87], v[104:105]
	v_pk_fma_f32 v[78:79], v[76:77], v[78:79], v[102:103]
	v_pk_fma_f32 v[86:87], v[90:91], v[92:93], v[100:101]
	global_store_dwordx4 v[94:95], v[78:81], off
	global_store_dwordx4 v[94:95], v[84:87], off offset:16
	v_cvt_pk_bf16_f32 v88, v78, v79
	v_mul_f32_e32 v79, v79, v79
	v_fmac_f32_e32 v79, v78, v78
	v_mul_f32_e32 v78, v81, v81
	v_fmac_f32_e32 v78, v80, v80
	v_cvt_pk_bf16_f32 v89, v80, v81
	v_add_f32_e32 v78, v79, v78
	v_mul_f32_e32 v79, v85, v85
	v_mul_f32_e32 v80, v87, v87
	v_fmac_f32_e32 v79, v84, v84
	v_fmac_f32_e32 v80, v86, v86
	v_add_f32_e32 v79, v79, v80
	v_add_f32_e32 v92, v78, v79
	v_pk_mul_f32 v[78:79], v[68:69], v[176:177] op_sel_hi:[1,0]
	v_pk_mul_f32 v[80:81], v[66:67], v[176:177] op_sel_hi:[1,0]
	v_mov_b32_e32 v66, v224
	v_mov_b32_e32 v67, v225
	v_mov_b32_e32 v68, v226
	v_mov_b32_e32 v69, v227
	v_lshl_add_u64 v[76:77], s[66:67], 0, v[82:83]
	v_cvt_pk_bf16_f32 v90, v84, v85
	v_rcp_f32_e32 v74, v70
	v_mul_f32_e32 v70, 0xbfb8aa3b, v71
	v_exp_f32_e32 v70, v70
	v_cvt_pk_bf16_f32 v91, v86, v87
	v_lshl_add_u64 v[76:77], v[76:77], 0, v[160:161]
	global_store_dwordx4 v[76:77], v[88:91], off
	v_add_f32_e32 v70, 1.0, v70
	v_rcp_f32_e32 v75, v70
	s_waitcnt vmcnt(1)
	v_lshlrev_b32_e32 v82, 16, v66
	v_and_b32_e32 v83, 0xffff0000, v66
	v_mul_f32_e32 v66, 0xbfb8aa3b, v72
	v_exp_f32_e32 v66, v66
	v_lshlrev_b32_e32 v86, 16, v67
	v_and_b32_e32 v87, 0xffff0000, v67
	v_lshlrev_b32_e32 v88, 16, v68
	v_add_f32_e32 v66, 1.0, v66
	v_rcp_f32_e32 v84, v66
	v_mul_f32_e32 v66, 0xbfb8aa3b, v73
	v_exp_f32_e32 v66, v66
	v_and_b32_e32 v89, 0xffff0000, v68
	v_lshlrev_b32_e32 v90, 16, v69
	v_and_b32_e32 v91, 0xffff0000, v69
	v_add_f32_e32 v66, 1.0, v66
	v_rcp_f32_e32 v85, v66
	v_mul_f32_e32 v66, 0xbfb8aa3b, v80
	v_exp_f32_e32 v66, v66
	s_nop 0
	v_add_f32_e32 v66, 1.0, v66
	v_rcp_f32_e32 v80, v66
	v_mul_f32_e32 v66, 0xbfb8aa3b, v81
	v_exp_f32_e32 v66, v66
	s_nop 0
	v_add_f32_e32 v66, 1.0, v66
	v_rcp_f32_e32 v81, v66
	v_mul_f32_e32 v66, 0xbfb8aa3b, v78
	v_exp_f32_e32 v66, v66
	s_nop 0
	v_add_f32_e32 v66, 1.0, v66
	v_rcp_f32_e32 v78, v66
	v_mul_f32_e32 v66, 0xbfb8aa3b, v79
	v_exp_f32_e32 v66, v66
	s_nop 0
	v_add_f32_e32 v66, 1.0, v66
	v_rcp_f32_e32 v79, v66
	v_add_u32_e32 v218, 0x40000, v217
	global_load_dwordx4 v[220:223], v218, s[12:13]
	global_load_dwordx4 v[66:69], v[94:95], off offset:528
	global_load_dwordx4 v[70:73], v[94:95], off offset:512
	s_waitcnt vmcnt(1)
	v_pk_fma_f32 v[66:67], v[80:81], v[88:89], v[66:67]
	s_waitcnt vmcnt(0)
	v_pk_fma_f32 v[72:73], v[84:85], v[86:87], v[72:73]
	v_pk_fma_f32 v[70:71], v[74:75], v[82:83], v[70:71]
	v_pk_fma_f32 v[68:69], v[78:79], v[90:91], v[68:69]
	global_store_dwordx4 v[94:95], v[70:73], off offset:512
	global_store_dwordx4 v[94:95], v[66:69], off offset:528
	v_cvt_pk_bf16_f32 v78, v70, v71
	v_cvt_pk_bf16_f32 v80, v66, v67
	v_mul_f32_e32 v71, v71, v71
	v_mul_f32_e32 v67, v67, v67
	v_fmac_f32_e32 v71, v70, v70
	v_mul_f32_e32 v70, v73, v73
	v_fmac_f32_e32 v67, v66, v66
	v_mul_f32_e32 v66, v69, v69
	v_fmac_f32_e32 v70, v72, v72
	v_fmac_f32_e32 v66, v68, v68
	v_add_f32_e32 v70, v71, v70
	v_add_f32_e32 v66, v67, v66
	v_cvt_pk_bf16_f32 v79, v72, v73
	v_cvt_pk_bf16_f32 v81, v68, v69
	v_add_f32_e32 v66, v70, v66
	v_lshlrev_b64 v[68:69], 11, v[172:173]
	global_store_dwordx4 v[76:77], v[78:81], off offset:256
	v_add_f32_e32 v88, v92, v66
	v_lshl_add_u64 v[66:67], s[12:13], 0, v[68:69]
	v_lshl_add_u64 v[66:67], v[66:67], 0, v[160:161]
	v_mov_b32_e32 v84, v220
	v_mov_b32_e32 v85, v221
	v_mov_b32_e32 v86, v222
	v_mov_b32_e32 v87, v223
	v_rcp_f32_e32 v78, v58
	v_mul_f32_e32 v58, 0xbfb8aa3b, v59
	v_exp_f32_e32 v58, v58
	v_rcp_f32_e32 v72, v62
	v_mul_f32_e32 v62, 0xbfb8aa3b, v63
	v_exp_f32_e32 v62, v62
	v_add_f32_e32 v58, 1.0, v58
	v_rcp_f32_e32 v79, v58
	v_mul_f32_e32 v58, 0xbfb8aa3b, v60
	v_exp_f32_e32 v58, v58
	v_add_f32_e32 v62, 1.0, v62
	v_rcp_f32_e32 v73, v62
	v_mul_f32_e32 v62, 0xbfb8aa3b, v64
	v_exp_f32_e32 v62, v62
	v_add_f32_e32 v58, 1.0, v58
	v_add_f32_e32 v62, 1.0, v62
	v_rcp_f32_e32 v76, v62
	v_mul_f32_e32 v62, 0xbfb8aa3b, v65
	v_exp_f32_e32 v62, v62
	s_waitcnt vmcnt(0)
	v_lshlrev_b32_e32 v74, 16, v84
	v_and_b32_e32 v75, 0xffff0000, v84
	v_rcp_f32_e32 v84, v58
	v_mul_f32_e32 v58, 0xbfb8aa3b, v61
	v_exp_f32_e32 v58, v58
	v_lshlrev_b32_e32 v80, 16, v85
	v_and_b32_e32 v81, 0xffff0000, v85
	v_add_f32_e32 v62, 1.0, v62
	v_add_f32_e32 v58, 1.0, v58
	v_rcp_f32_e32 v85, v58
	v_lshlrev_b64 v[58:59], 12, v[172:173]
	v_lshl_add_u64 v[58:59], s[6:7], 0, v[58:59]
	v_lshl_add_u64 v[70:71], v[58:59], 0, v[164:165]
	v_rcp_f32_e32 v77, v62
	v_add_u32_e32 v218, 0x40000, v217
	global_load_dwordx4 v[224:227], v218, s[12:13] offset:256
	global_load_dwordx4 v[58:61], v[70:71], off offset:16
	global_load_dwordx4 v[62:65], v[70:71], off
	v_lshlrev_b32_e32 v82, 16, v86
	v_and_b32_e32 v83, 0xffff0000, v86
	v_lshlrev_b32_e32 v86, 16, v87
	v_and_b32_e32 v87, 0xffff0000, v87
	s_waitcnt vmcnt(0)
	v_pk_fma_f32 v[64:65], v[76:77], v[80:81], v[64:65]
	v_pk_fma_f32 v[62:63], v[72:73], v[74:75], v[62:63]
	v_pk_fma_f32 v[74:75], v[84:85], v[86:87], v[60:61]
	v_mul_f32_e32 v60, v63, v63
	v_mul_f32_e32 v61, v65, v65
	v_pk_fma_f32 v[72:73], v[78:79], v[82:83], v[58:59]
	v_fmac_f32_e32 v60, v62, v62
	v_fmac_f32_e32 v61, v64, v64
	global_store_dwordx4 v[70:71], v[62:65], off
	global_store_dwordx4 v[70:71], v[72:75], off offset:16
	v_cvt_pk_bf16_f32 v76, v62, v63
	v_add_f32_e32 v60, v60, v61
	v_mul_f32_e32 v61, v73, v73
	v_mul_f32_e32 v62, v75, v75
	v_lshl_add_u64 v[58:59], s[66:67], 0, v[68:69]
	v_fmac_f32_e32 v61, v72, v72
	v_fmac_f32_e32 v62, v74, v74
	v_cvt_pk_bf16_f32 v77, v64, v65
	v_cvt_pk_bf16_f32 v78, v72, v73
	v_cvt_pk_bf16_f32 v79, v74, v75
	v_lshl_add_u64 v[58:59], v[58:59], 0, v[160:161]
	v_add_f32_e32 v61, v61, v62
	global_store_dwordx4 v[58:59], v[76:79], off
	v_pk_mul_f32 v[62:63], v[50:51], v[174:175] op_sel_hi:[1,0]
	v_rcp_f32_e32 v64, v54
	v_add_f32_e32 v78, v60, v61
	v_pk_mul_f32 v[60:61], v[52:53], v[174:175] op_sel_hi:[1,0]
	v_mov_b32_e32 v50, v224
	v_mov_b32_e32 v51, v225
	v_mov_b32_e32 v52, v226
	v_mov_b32_e32 v53, v227
	v_mul_f32_e32 v54, 0xbfb8aa3b, v55
	v_exp_f32_e32 v54, v54
	s_waitcnt vmcnt(0)
; __device__ __forceinline__ unsigned cvtpk(float lo, float hi) { f32x2 v = {lo, hi}; bf16x2_t b = __builtin_convertvector(v, bf16x2_t); return __builtin_bit_cast(unsigned, b); }
; __device__ __forceinline__ float sigmoidf_(float v) { return __builtin_amdgcn_rcpf(1.0f + __expf(-v)); }
; #define EPI_LOOP_ROWS for (int ai = 0; ai < 2; ++ai) _Pragma("unroll") for (int m = 0; m < 4; ++m)
;     __device__ __forceinline__ void operator()(const f32x4 (&acc)[2][2][4][2], const Unit& u, int wv) const {
;     ...
;         EPI_LOOP_ROWS { const size_t row = (size_t)(row0 + ai * HALF + m * 16);
;             const float rstd = rs[ai][m]; float ssq = 0.f;
; #pragma unroll
;             for (int bj = 0; bj < 2; ++bj) { const int col = col0 + bj * HALF;
;                 f32x4 v0 = acc[ai][bj][m][0] * rstd, v1 = acc[ai][bj][m][1] * rstd;
;                 if (PP) { const u32x4 g = *(const u32x4*)(PP + row * 1024 + col);
;                     v0[0] = sigmoidf_(v0[0]) * __builtin_bit_cast(float, g.x << 16); v0[1] = sigmoidf_(v0[1]) * __builtin_bit_cast(float, g.x & 0xffff0000u);
;                     v0[2] = sigmoidf_(v0[2]) * __builtin_bit_cast(float, g.y << 16); v0[3] = sigmoidf_(v0[3]) * __builtin_bit_cast(float, g.y & 0xffff0000u);
;                     v1[0] = sigmoidf_(v1[0]) * __builtin_bit_cast(float, g.z << 16); v1[1] = sigmoidf_(v1[1]) * __builtin_bit_cast(float, g.z & 0xffff0000u);
;                     v1[2] = sigmoidf_(v1[2]) * __builtin_bit_cast(float, g.w << 16); v1[3] = sigmoidf_(v1[3]) * __builtin_bit_cast(float, g.w & 0xffff0000u); }
;                 float* xp = X + row * 1024 + col;
;                 v0 += *(const f32x4*)xp; v1 += *(const f32x4*)(xp + 4);
;                 *(f32x4*)xp = v0; *(f32x4*)(xp + 4) = v1;
;                 u32x4 w; w.x = cvtpk(v0[0], v0[1]); w.y = cvtpk(v0[2], v0[3]); w.z = cvtpk(v1[0], v1[1]); w.w = cvtpk(v1[2], v1[3]);
;                 *(u32x4*)(XB + row * 1024 + col) = w;
;                 ssq += ((v0[0] * v0[0] + v0[1] * v0[1]) + (v0[2] * v0[2] + v0[3] * v0[3])) + ((v1[0] * v1[0] + v1[1] * v1[1]) + (v1[2] * v1[2] + v1[3] * v1[3])); }
;             sq[ai][m] = ssq;
	v_lshlrev_b32_e32 v66, 16, v50
	v_and_b32_e32 v67, 0xffff0000, v50
	v_mul_f32_e32 v50, 0xbfb8aa3b, v56
	v_exp_f32_e32 v50, v50
	v_add_f32_e32 v54, 1.0, v54
	v_rcp_f32_e32 v65, v54
	v_lshlrev_b32_e32 v72, 16, v51
	v_add_f32_e32 v50, 1.0, v50
	v_rcp_f32_e32 v68, v50
	v_mul_f32_e32 v50, 0xbfb8aa3b, v57
	v_exp_f32_e32 v50, v50
	v_and_b32_e32 v73, 0xffff0000, v51
	v_lshlrev_b32_e32 v74, 16, v52
	v_and_b32_e32 v75, 0xffff0000, v52
	v_add_f32_e32 v50, 1.0, v50
	v_rcp_f32_e32 v69, v50
	v_mul_f32_e32 v50, 0xbfb8aa3b, v62
	v_exp_f32_e32 v50, v50
	v_lshlrev_b32_e32 v76, 16, v53
	v_and_b32_e32 v77, 0xffff0000, v53
	v_add_f32_e32 v50, 1.0, v50
	v_rcp_f32_e32 v62, v50
	v_mul_f32_e32 v50, 0xbfb8aa3b, v63
	v_exp_f32_e32 v50, v50
	s_nop 0
	v_add_f32_e32 v50, 1.0, v50
	v_rcp_f32_e32 v63, v50
	v_mul_f32_e32 v50, 0xbfb8aa3b, v60
	v_exp_f32_e32 v50, v50
	s_nop 0
	v_add_f32_e32 v50, 1.0, v50
	v_rcp_f32_e32 v60, v50
	v_mul_f32_e32 v50, 0xbfb8aa3b, v61
	v_exp_f32_e32 v50, v50
	s_nop 0
	v_add_f32_e32 v50, 1.0, v50
	v_rcp_f32_e32 v61, v50
	v_add_u32_e32 v218, 0x48000, v217
	global_load_dwordx4 v[220:223], v218, s[12:13]
	global_load_dwordx4 v[50:53], v[70:71], off offset:528
	global_load_dwordx4 v[54:57], v[70:71], off offset:512
	s_waitcnt vmcnt(1)
	v_pk_fma_f32 v[50:51], v[62:63], v[74:75], v[50:51]
	s_waitcnt vmcnt(0)
	v_pk_fma_f32 v[56:57], v[68:69], v[72:73], v[56:57]
	v_pk_fma_f32 v[54:55], v[64:65], v[66:67], v[54:55]
	v_pk_fma_f32 v[52:53], v[60:61], v[76:77], v[52:53]
	global_store_dwordx4 v[70:71], v[54:57], off offset:512
	global_store_dwordx4 v[70:71], v[50:53], off offset:528
	v_cvt_pk_bf16_f32 v60, v54, v55
	v_cvt_pk_bf16_f32 v62, v50, v51
	v_mul_f32_e32 v55, v55, v55
	v_mul_f32_e32 v51, v51, v51
	v_fmac_f32_e32 v55, v54, v54
	v_mul_f32_e32 v54, v57, v57
	v_fmac_f32_e32 v51, v50, v50
	v_mul_f32_e32 v50, v53, v53
	v_fmac_f32_e32 v54, v56, v56
	v_fmac_f32_e32 v50, v52, v52
	v_add_f32_e32 v54, v55, v54
	v_add_f32_e32 v50, v51, v50
	v_add_f32_e32 v50, v54, v50
	v_cvt_pk_bf16_f32 v61, v56, v57
	v_cvt_pk_bf16_f32 v63, v52, v53
	v_add_f32_e32 v52, v78, v50
	v_lshlrev_b64 v[50:51], 11, v[168:169]
	global_store_dwordx4 v[58:59], v[60:63], off offset:256
	v_pk_mul_f32 v[58:59], v[42:43], v[170:171] op_sel_hi:[1,0]
	v_lshl_add_u64 v[42:43], s[12:13], 0, v[50:51]
	v_lshl_add_u64 v[42:43], v[42:43], 0, v[160:161]
	v_pk_mul_f32 v[54:55], v[46:47], v[170:171] op_sel_hi:[1,0]
	v_pk_mul_f32 v[56:57], v[44:45], v[170:171] op_sel_hi:[1,0]
	v_mov_b32_e32 v44, v220
	v_mov_b32_e32 v45, v221
	v_mov_b32_e32 v46, v222
	v_mov_b32_e32 v47, v223
	v_mul_f32_e32 v53, 0xbfb8aa3b, v54
	v_exp_f32_e32 v53, v53
	s_waitcnt vmcnt(0)
	v_lshlrev_b32_e32 v62, 16, v44
	v_and_b32_e32 v63, 0xffff0000, v44
	v_mul_f32_e32 v44, 0xbfb8aa3b, v48
	v_exp_f32_e32 v44, v44
	v_lshlrev_b32_e32 v64, 16, v45
	v_and_b32_e32 v65, 0xffff0000, v45
	v_add_f32_e32 v53, 1.0, v53
	v_add_f32_e32 v44, 1.0, v44
	v_rcp_f32_e32 v48, v44
	v_mul_f32_e32 v44, 0xbfb8aa3b, v49
	v_exp_f32_e32 v44, v44
	v_rcp_f32_e32 v60, v53
	v_mul_f32_e32 v53, 0xbfb8aa3b, v55
	v_lshlrev_b32_e32 v66, 16, v46
	v_add_f32_e32 v44, 1.0, v44
	v_rcp_f32_e32 v49, v44
	v_mul_f32_e32 v44, 0xbfb8aa3b, v58
	v_exp_f32_e32 v44, v44
	v_and_b32_e32 v67, 0xffff0000, v46
	v_lshlrev_b32_e32 v70, 16, v47
	v_and_b32_e32 v71, 0xffff0000, v47
	v_add_f32_e32 v44, 1.0, v44
	v_rcp_f32_e32 v58, v44
	v_mul_f32_e32 v44, 0xbfb8aa3b, v59
	v_exp_f32_e32 v44, v44
	v_exp_f32_e32 v53, v53
	v_add_f32_e32 v44, 1.0, v44
	v_rcp_f32_e32 v59, v44
	v_mul_f32_e32 v44, 0xbfb8aa3b, v56
	v_exp_f32_e32 v44, v44
	v_add_f32_e32 v53, 1.0, v53
	v_rcp_f32_e32 v61, v53
	v_add_f32_e32 v44, 1.0, v44
	v_rcp_f32_e32 v68, v44
	v_mul_f32_e32 v44, 0xbfb8aa3b, v57
	v_exp_f32_e32 v44, v44
	s_nop 0
	v_add_f32_e32 v44, 1.0, v44
	v_rcp_f32_e32 v69, v44
	v_lshlrev_b64 v[44:45], 12, v[168:169]
	v_lshl_add_u64 v[44:45], s[6:7], 0, v[44:45]
	v_lshl_add_u64 v[72:73], v[44:45], 0, v[164:165]
	v_add_u32_e32 v218, 0x48000, v217
	global_load_dwordx4 v[224:227], v218, s[12:13] offset:256
	global_load_dwordx4 v[44:47], v[72:73], off offset:16
	global_load_dwordx4 v[54:57], v[72:73], off
	s_waitcnt vmcnt(1)
	v_pk_fma_f32 v[44:45], v[58:59], v[66:67], v[44:45]
	s_waitcnt vmcnt(0)
	v_pk_fma_f32 v[56:57], v[48:49], v[64:65], v[56:57]
	v_pk_fma_f32 v[54:55], v[60:61], v[62:63], v[54:55]
	v_pk_fma_f32 v[46:47], v[68:69], v[70:71], v[46:47]
	global_store_dwordx4 v[72:73], v[54:57], off
	global_store_dwordx4 v[72:73], v[44:47], off offset:16
	v_cvt_pk_bf16_f32 v60, v44, v45
	v_lshl_add_u64 v[48:49], s[66:67], 0, v[50:51]
	v_mul_f32_e32 v45, v45, v45
	v_mul_f32_e32 v50, v55, v55
	v_mul_f32_e32 v51, v57, v57
	v_fmac_f32_e32 v45, v44, v44
	v_mul_f32_e32 v44, v47, v47
	v_fmac_f32_e32 v50, v54, v54
	v_fmac_f32_e32 v51, v56, v56
	v_fmac_f32_e32 v44, v46, v46
	v_add_f32_e32 v50, v50, v51
	v_add_f32_e32 v44, v45, v44
	v_cvt_pk_bf16_f32 v61, v46, v47
	v_add_f32_e32 v53, v50, v44
	v_pk_mul_f32 v[44:45], v[36:37], v[170:171] op_sel_hi:[1,0]
	v_pk_mul_f32 v[46:47], v[34:35], v[170:171] op_sel_hi:[1,0]
	v_mov_b32_e32 v34, v224
	v_mov_b32_e32 v35, v225
	v_mov_b32_e32 v36, v226
	v_mov_b32_e32 v37, v227
	v_cvt_pk_bf16_f32 v58, v54, v55
	v_rcp_f32_e32 v42, v38
	v_mul_f32_e32 v38, 0xbfb8aa3b, v39
	v_exp_f32_e32 v38, v38
	v_cvt_pk_bf16_f32 v59, v56, v57
	v_lshl_add_u64 v[48:49], v[48:49], 0, v[160:161]
	global_store_dwordx4 v[48:49], v[58:61], off
	v_add_f32_e32 v38, 1.0, v38
	v_rcp_f32_e32 v43, v38
	s_waitcnt vmcnt(1)
; __device__ __forceinline__ unsigned cvtpk(float lo, float hi) { f32x2 v = {lo, hi}; bf16x2_t b = __builtin_convertvector(v, bf16x2_t); return __builtin_bit_cast(unsigned, b); }
; __device__ __forceinline__ float sigmoidf_(float v) { return __builtin_amdgcn_rcpf(1.0f + __expf(-v)); }
; #define EPI_LOOP_ROWS for (int ai = 0; ai < 2; ++ai) _Pragma("unroll") for (int m = 0; m < 4; ++m)
;     __device__ __forceinline__ void operator()(const f32x4 (&acc)[2][2][4][2], const Unit& u, int wv) const {
;     ...
;         EPI_LOOP_ROWS { const size_t row = (size_t)(row0 + ai * HALF + m * 16);
;             const float rstd = rs[ai][m]; float ssq = 0.f;
; #pragma unroll
;             for (int bj = 0; bj < 2; ++bj) { const int col = col0 + bj * HALF;
;                 f32x4 v0 = acc[ai][bj][m][0] * rstd, v1 = acc[ai][bj][m][1] * rstd;
;                 if (PP) { const u32x4 g = *(const u32x4*)(PP + row * 1024 + col);
;                     v0[0] = sigmoidf_(v0[0]) * __builtin_bit_cast(float, g.x << 16); v0[1] = sigmoidf_(v0[1]) * __builtin_bit_cast(float, g.x & 0xffff0000u);
;                     v0[2] = sigmoidf_(v0[2]) * __builtin_bit_cast(float, g.y << 16); v0[3] = sigmoidf_(v0[3]) * __builtin_bit_cast(float, g.y & 0xffff0000u);
;                     v1[0] = sigmoidf_(v1[0]) * __builtin_bit_cast(float, g.z << 16); v1[1] = sigmoidf_(v1[1]) * __builtin_bit_cast(float, g.z & 0xffff0000u);
;                     v1[2] = sigmoidf_(v1[2]) * __builtin_bit_cast(float, g.w << 16); v1[3] = sigmoidf_(v1[3]) * __builtin_bit_cast(float, g.w & 0xffff0000u); }
;                 float* xp = X + row * 1024 + col;
;                 v0 += *(const f32x4*)xp; v1 += *(const f32x4*)(xp + 4);
;                 *(f32x4*)xp = v0; *(f32x4*)(xp + 4) = v1;
;                 u32x4 w; w.x = cvtpk(v0[0], v0[1]); w.y = cvtpk(v0[2], v0[3]); w.z = cvtpk(v1[0], v1[1]); w.w = cvtpk(v1[2], v1[3]);
;                 *(u32x4*)(XB + row * 1024 + col) = w;
;                 ssq += ((v0[0] * v0[0] + v0[1] * v0[1]) + (v0[2] * v0[2] + v0[3] * v0[3])) + ((v1[0] * v1[0] + v1[1] * v1[1]) + (v1[2] * v1[2] + v1[3] * v1[3])); }
;             sq[ai][m] = ssq;
	v_lshlrev_b32_e32 v50, 16, v34
	v_and_b32_e32 v51, 0xffff0000, v34
	v_mul_f32_e32 v34, 0xbfb8aa3b, v40
	v_exp_f32_e32 v34, v34
	v_lshlrev_b32_e32 v56, 16, v35
	v_and_b32_e32 v57, 0xffff0000, v35
	v_lshlrev_b32_e32 v58, 16, v36
	v_add_f32_e32 v34, 1.0, v34
	v_rcp_f32_e32 v54, v34
	v_mul_f32_e32 v34, 0xbfb8aa3b, v41
	v_exp_f32_e32 v34, v34
	v_and_b32_e32 v59, 0xffff0000, v36
	v_lshlrev_b32_e32 v60, 16, v37
	v_and_b32_e32 v61, 0xffff0000, v37
	v_add_f32_e32 v34, 1.0, v34
	v_rcp_f32_e32 v55, v34
	v_mul_f32_e32 v34, 0xbfb8aa3b, v46
	v_exp_f32_e32 v34, v34
	s_nop 0
	v_add_f32_e32 v34, 1.0, v34
	v_rcp_f32_e32 v46, v34
	v_mul_f32_e32 v34, 0xbfb8aa3b, v47
	v_exp_f32_e32 v34, v34
	s_nop 0
	v_add_f32_e32 v34, 1.0, v34
	v_rcp_f32_e32 v47, v34
	v_mul_f32_e32 v34, 0xbfb8aa3b, v44
	v_exp_f32_e32 v34, v34
	s_nop 0
	v_add_f32_e32 v34, 1.0, v34
	v_rcp_f32_e32 v44, v34
	v_mul_f32_e32 v34, 0xbfb8aa3b, v45
	v_exp_f32_e32 v34, v34
	s_nop 0
	v_add_f32_e32 v34, 1.0, v34
	v_rcp_f32_e32 v45, v34
	v_add_u32_e32 v218, 0x50000, v217
	global_load_dwordx4 v[220:223], v218, s[12:13]
	global_load_dwordx4 v[34:37], v[72:73], off offset:528
	global_load_dwordx4 v[38:41], v[72:73], off offset:512
	s_waitcnt vmcnt(1)
	v_pk_fma_f32 v[34:35], v[46:47], v[58:59], v[34:35]
	s_waitcnt vmcnt(0)
	v_pk_fma_f32 v[40:41], v[54:55], v[56:57], v[40:41]
	v_pk_fma_f32 v[38:39], v[42:43], v[50:51], v[38:39]
	v_pk_fma_f32 v[36:37], v[44:45], v[60:61], v[36:37]
	global_store_dwordx4 v[72:73], v[38:41], off offset:512
	global_store_dwordx4 v[72:73], v[34:37], off offset:528
	v_cvt_pk_bf16_f32 v42, v38, v39
	v_cvt_pk_bf16_f32 v44, v34, v35
	v_mul_f32_e32 v39, v39, v39
	v_mul_f32_e32 v35, v35, v35
	v_fmac_f32_e32 v39, v38, v38
	v_mul_f32_e32 v38, v41, v41
	v_fmac_f32_e32 v35, v34, v34
	v_mul_f32_e32 v34, v37, v37
	v_fmac_f32_e32 v38, v40, v40
	v_fmac_f32_e32 v34, v36, v36
	v_add_f32_e32 v38, v39, v38
	v_add_f32_e32 v34, v35, v34
	v_add_f32_e32 v34, v38, v34
	v_cvt_pk_bf16_f32 v43, v40, v41
	v_cvt_pk_bf16_f32 v45, v36, v37
	v_add_f32_e32 v36, v53, v34
	v_lshlrev_b64 v[34:35], 11, v[162:163]
	global_store_dwordx4 v[48:49], v[42:45], off offset:256
	v_pk_mul_f32 v[38:39], v[30:31], v[166:167] op_sel_hi:[1,0]
	v_pk_mul_f32 v[40:41], v[28:29], v[166:167] op_sel_hi:[1,0]
	v_pk_mul_f32 v[42:43], v[26:27], v[166:167] op_sel_hi:[1,0]
	v_lshl_add_u64 v[26:27], s[12:13], 0, v[34:35]
	v_lshl_add_u64 v[26:27], v[26:27], 0, v[160:161]
	v_mov_b32_e32 v28, v220
	v_mov_b32_e32 v29, v221
	v_mov_b32_e32 v30, v222
	v_mov_b32_e32 v31, v223
	v_mul_f32_e32 v37, 0xbfb8aa3b, v38
	v_exp_f32_e32 v37, v37
	s_waitcnt vmcnt(0)
	v_lshlrev_b32_e32 v46, 16, v28
	v_and_b32_e32 v47, 0xffff0000, v28
	v_mul_f32_e32 v28, 0xbfb8aa3b, v32
	v_exp_f32_e32 v28, v28
	v_lshlrev_b32_e32 v48, 16, v29
	v_and_b32_e32 v49, 0xffff0000, v29
	v_add_f32_e32 v37, 1.0, v37
	v_add_f32_e32 v28, 1.0, v28
	v_rcp_f32_e32 v32, v28
	v_mul_f32_e32 v28, 0xbfb8aa3b, v33
	v_exp_f32_e32 v28, v28
	v_rcp_f32_e32 v44, v37
	v_mul_f32_e32 v37, 0xbfb8aa3b, v39
	v_lshlrev_b32_e32 v50, 16, v30
	v_add_f32_e32 v28, 1.0, v28
	v_rcp_f32_e32 v33, v28
	v_mul_f32_e32 v28, 0xbfb8aa3b, v42
	v_exp_f32_e32 v28, v28
	v_and_b32_e32 v51, 0xffff0000, v30
	v_lshlrev_b32_e32 v56, 16, v31
	v_and_b32_e32 v57, 0xffff0000, v31
	v_add_f32_e32 v28, 1.0, v28
	v_rcp_f32_e32 v42, v28
	v_mul_f32_e32 v28, 0xbfb8aa3b, v43
	v_exp_f32_e32 v28, v28
	v_exp_f32_e32 v37, v37
	v_add_f32_e32 v28, 1.0, v28
	v_rcp_f32_e32 v43, v28
	v_mul_f32_e32 v28, 0xbfb8aa3b, v40
	v_exp_f32_e32 v28, v28
	v_add_f32_e32 v37, 1.0, v37
	v_rcp_f32_e32 v45, v37
	v_add_f32_e32 v28, 1.0, v28
	v_rcp_f32_e32 v54, v28
	v_mul_f32_e32 v28, 0xbfb8aa3b, v41
	v_exp_f32_e32 v28, v28
	s_nop 0
	v_add_f32_e32 v28, 1.0, v28
	v_rcp_f32_e32 v55, v28
	v_lshlrev_b64 v[28:29], 12, v[162:163]
	v_lshl_add_u64 v[28:29], s[6:7], 0, v[28:29]
	v_lshl_add_u64 v[58:59], v[28:29], 0, v[164:165]
	v_add_u32_e32 v218, 0x50000, v217
	global_load_dwordx4 v[224:227], v218, s[12:13] offset:256
	global_load_dwordx4 v[28:31], v[58:59], off offset:16
	global_load_dwordx4 v[38:41], v[58:59], off
	s_waitcnt vmcnt(1)
	v_pk_fma_f32 v[28:29], v[42:43], v[50:51], v[28:29]
	s_waitcnt vmcnt(0)
	v_pk_fma_f32 v[40:41], v[32:33], v[48:49], v[40:41]
	v_pk_fma_f32 v[38:39], v[44:45], v[46:47], v[38:39]
	v_pk_fma_f32 v[30:31], v[54:55], v[56:57], v[30:31]
	global_store_dwordx4 v[58:59], v[38:41], off
	global_store_dwordx4 v[58:59], v[28:31], off offset:16
	v_cvt_pk_bf16_f32 v44, v28, v29
	v_lshl_add_u64 v[32:33], s[66:67], 0, v[34:35]
	v_mul_f32_e32 v29, v29, v29
	v_mul_f32_e32 v34, v39, v39
	v_mul_f32_e32 v35, v41, v41
	v_fmac_f32_e32 v29, v28, v28
	v_mul_f32_e32 v28, v31, v31
	v_fmac_f32_e32 v34, v38, v38
	v_fmac_f32_e32 v35, v40, v40
	v_fmac_f32_e32 v28, v30, v30
	v_add_f32_e32 v34, v34, v35
	v_add_f32_e32 v28, v29, v28
	v_cvt_pk_bf16_f32 v45, v30, v31
	v_add_f32_e32 v37, v34, v28
	v_pk_mul_f32 v[28:29], v[20:21], v[166:167] op_sel_hi:[1,0]
	v_pk_mul_f32 v[30:31], v[18:19], v[166:167] op_sel_hi:[1,0]
	v_mov_b32_e32 v18, v224
	v_mov_b32_e32 v19, v225
	v_mov_b32_e32 v20, v226
	v_mov_b32_e32 v21, v227
	v_cvt_pk_bf16_f32 v42, v38, v39
	v_rcp_f32_e32 v26, v22
	v_mul_f32_e32 v22, 0xbfb8aa3b, v23
	v_exp_f32_e32 v22, v22
	v_cvt_pk_bf16_f32 v43, v40, v41
	v_lshl_add_u64 v[32:33], v[32:33], 0, v[160:161]
	global_store_dwordx4 v[32:33], v[42:45], off
	v_add_f32_e32 v22, 1.0, v22
	v_rcp_f32_e32 v27, v22
	s_waitcnt vmcnt(1)
; __device__ __forceinline__ unsigned cvtpk(float lo, float hi) { f32x2 v = {lo, hi}; bf16x2_t b = __builtin_convertvector(v, bf16x2_t); return __builtin_bit_cast(unsigned, b); }
; __device__ __forceinline__ float sigmoidf_(float v) { return __builtin_amdgcn_rcpf(1.0f + __expf(-v)); }
; #define EPI_LOOP_ROWS for (int ai = 0; ai < 2; ++ai) _Pragma("unroll") for (int m = 0; m < 4; ++m)
;     __device__ __forceinline__ void operator()(const f32x4 (&acc)[2][2][4][2], const Unit& u, int wv) const {
;     ...
;         EPI_LOOP_ROWS { const size_t row = (size_t)(row0 + ai * HALF + m * 16);
;             const float rstd = rs[ai][m]; float ssq = 0.f;
; #pragma unroll
;             for (int bj = 0; bj < 2; ++bj) { const int col = col0 + bj * HALF;
;                 f32x4 v0 = acc[ai][bj][m][0] * rstd, v1 = acc[ai][bj][m][1] * rstd;
;                 if (PP) { const u32x4 g = *(const u32x4*)(PP + row * 1024 + col);
;                     v0[0] = sigmoidf_(v0[0]) * __builtin_bit_cast(float, g.x << 16); v0[1] = sigmoidf_(v0[1]) * __builtin_bit_cast(float, g.x & 0xffff0000u);
;                     v0[2] = sigmoidf_(v0[2]) * __builtin_bit_cast(float, g.y << 16); v0[3] = sigmoidf_(v0[3]) * __builtin_bit_cast(float, g.y & 0xffff0000u);
;                     v1[0] = sigmoidf_(v1[0]) * __builtin_bit_cast(float, g.z << 16); v1[1] = sigmoidf_(v1[1]) * __builtin_bit_cast(float, g.z & 0xffff0000u);
;                     v1[2] = sigmoidf_(v1[2]) * __builtin_bit_cast(float, g.w << 16); v1[3] = sigmoidf_(v1[3]) * __builtin_bit_cast(float, g.w & 0xffff0000u); }
;                 float* xp = X + row * 1024 + col;
;                 v0 += *(const f32x4*)xp; v1 += *(const f32x4*)(xp + 4);
;                 *(f32x4*)xp = v0; *(f32x4*)(xp + 4) = v1;
;                 u32x4 w; w.x = cvtpk(v0[0], v0[1]); w.y = cvtpk(v0[2], v0[3]); w.z = cvtpk(v1[0], v1[1]); w.w = cvtpk(v1[2], v1[3]);
;                 *(u32x4*)(XB + row * 1024 + col) = w;
;                 ssq += ((v0[0] * v0[0] + v0[1] * v0[1]) + (v0[2] * v0[2] + v0[3] * v0[3])) + ((v1[0] * v1[0] + v1[1] * v1[1]) + (v1[2] * v1[2] + v1[3] * v1[3])); }
;             sq[ai][m] = ssq;
	v_lshlrev_b32_e32 v34, 16, v18
	v_and_b32_e32 v35, 0xffff0000, v18
	v_mul_f32_e32 v18, 0xbfb8aa3b, v24
	v_exp_f32_e32 v18, v18
	v_lshlrev_b32_e32 v40, 16, v19
	v_and_b32_e32 v41, 0xffff0000, v19
	v_lshlrev_b32_e32 v42, 16, v20
	v_add_f32_e32 v18, 1.0, v18
	v_rcp_f32_e32 v38, v18
	v_mul_f32_e32 v18, 0xbfb8aa3b, v25
	v_exp_f32_e32 v18, v18
	v_and_b32_e32 v43, 0xffff0000, v20
	v_lshlrev_b32_e32 v44, 16, v21
	v_and_b32_e32 v45, 0xffff0000, v21
	v_add_f32_e32 v18, 1.0, v18
	v_rcp_f32_e32 v39, v18
	v_mul_f32_e32 v18, 0xbfb8aa3b, v30
	v_exp_f32_e32 v18, v18
	s_nop 0
	v_add_f32_e32 v18, 1.0, v18
	v_rcp_f32_e32 v30, v18
	v_mul_f32_e32 v18, 0xbfb8aa3b, v31
	v_exp_f32_e32 v18, v18
	s_nop 0
	v_add_f32_e32 v18, 1.0, v18
	v_rcp_f32_e32 v31, v18
	v_mul_f32_e32 v18, 0xbfb8aa3b, v28
	v_exp_f32_e32 v18, v18
	s_nop 0
	v_add_f32_e32 v18, 1.0, v18
	v_rcp_f32_e32 v28, v18
	v_mul_f32_e32 v18, 0xbfb8aa3b, v29
	v_exp_f32_e32 v18, v18
	s_nop 0
	v_add_f32_e32 v18, 1.0, v18
	v_rcp_f32_e32 v29, v18
	v_add_u32_e32 v218, 0x58000, v217
	global_load_dwordx4 v[220:223], v218, s[12:13]
	global_load_dwordx4 v[18:21], v[58:59], off offset:528
	global_load_dwordx4 v[22:25], v[58:59], off offset:512
	s_waitcnt vmcnt(1)
	v_pk_fma_f32 v[18:19], v[30:31], v[42:43], v[18:19]
	s_waitcnt vmcnt(0)
	v_pk_fma_f32 v[24:25], v[38:39], v[40:41], v[24:25]
	v_pk_fma_f32 v[22:23], v[26:27], v[34:35], v[22:23]
	v_pk_fma_f32 v[20:21], v[28:29], v[44:45], v[20:21]
	global_store_dwordx4 v[58:59], v[22:25], off offset:512
	global_store_dwordx4 v[58:59], v[18:21], off offset:528
	v_cvt_pk_bf16_f32 v26, v22, v23
	v_cvt_pk_bf16_f32 v28, v18, v19
	v_mul_f32_e32 v23, v23, v23
	v_mul_f32_e32 v19, v19, v19
	v_fmac_f32_e32 v23, v22, v22
	v_mul_f32_e32 v22, v25, v25
	v_fmac_f32_e32 v19, v18, v18
	v_mul_f32_e32 v18, v21, v21
	v_fmac_f32_e32 v22, v24, v24
	v_fmac_f32_e32 v18, v20, v20
	v_cvt_pk_bf16_f32 v27, v24, v25
	v_cvt_pk_bf16_f32 v29, v20, v21
	v_add_f32_e32 v22, v23, v22
	v_add_f32_e32 v18, v19, v18
	global_store_dwordx4 v[32:33], v[26:29], off offset:256
	v_add_f32_e32 v18, v22, v18
	v_pk_mul_f32 v[30:31], v[12:13], v[0:1] op_sel_hi:[1,0]
	v_lshlrev_b64 v[26:27], 11, v[158:159]
	v_add_f32_e32 v28, v37, v18
	v_pk_mul_f32 v[18:19], v[10:11], v[0:1] op_sel_hi:[1,0]
	v_lshl_add_u64 v[10:11], s[12:13], 0, v[26:27]
	v_lshl_add_u64 v[24:25], v[10:11], 0, v[160:161]
	v_mov_b32_e32 v20, v220
	v_mov_b32_e32 v21, v221
	v_mov_b32_e32 v22, v222
	v_mov_b32_e32 v23, v223
	v_mul_f32_e32 v10, 0xbfb8aa3b, v14
	v_mul_f32_e32 v11, 0xbfb8aa3b, v15
	v_mul_f32_e32 v14, 0xbfb8aa3b, v16
	v_mul_f32_e32 v15, 0xbfb8aa3b, v17
	v_mul_f32_e32 v18, 0xbfb8aa3b, v18
	v_mul_f32_e32 v19, 0xbfb8aa3b, v19
	v_exp_f32_e32 v10, v10
	v_exp_f32_e32 v11, v11
	v_exp_f32_e32 v14, v14
	v_exp_f32_e32 v15, v15
	v_exp_f32_e32 v18, v18
	v_exp_f32_e32 v19, v19
	v_add_f32_e32 v10, 1.0, v10
	v_add_f32_e32 v11, 1.0, v11
	v_add_f32_e32 v14, 1.0, v14
	v_add_f32_e32 v15, 1.0, v15
	v_add_f32_e32 v18, 1.0, v18
	v_add_f32_e32 v19, 1.0, v19
	v_rcp_f32_e32 v10, v10
	v_rcp_f32_e32 v11, v11
	v_rcp_f32_e32 v14, v14
	v_rcp_f32_e32 v15, v15
	v_rcp_f32_e32 v18, v18
	v_rcp_f32_e32 v19, v19
	v_lshl_add_u64 v[26:27], s[66:67], 0, v[26:27]
	v_lshl_add_u64 v[26:27], v[26:27], 0, v[160:161]
	s_waitcnt vmcnt(0)
	v_lshlrev_b32_e32 v12, 16, v20
	v_and_b32_e32 v13, 0xffff0000, v20
	v_lshlrev_b32_e32 v16, 16, v21
	v_and_b32_e32 v17, 0xffff0000, v21
	v_lshlrev_b32_e32 v20, 16, v22
	v_and_b32_e32 v21, 0xffff0000, v22
	v_mul_f32_e32 v22, 0xbfb8aa3b, v30
	v_exp_f32_e32 v22, v22
	v_lshlrev_b32_e32 v42, 16, v23
	v_and_b32_e32 v43, 0xffff0000, v23
	v_add_f32_e32 v22, 1.0, v22
	v_rcp_f32_e32 v34, v22
	v_mul_f32_e32 v22, 0xbfb8aa3b, v31
	v_exp_f32_e32 v22, v22
	s_nop 0
	v_add_f32_e32 v22, 1.0, v22
	v_rcp_f32_e32 v35, v22
	v_lshlrev_b64 v[22:23], 12, v[158:159]
	v_lshl_add_u64 v[22:23], s[6:7], 0, v[22:23]
	v_lshl_add_u64 v[22:23], v[22:23], 0, v[164:165]
	v_add_u32_e32 v218, 0x58000, v217
	global_load_dwordx4 v[224:227], v218, s[12:13] offset:256
	global_load_dwordx4 v[30:33], v[22:23], off offset:16
	global_load_dwordx4 v[38:41], v[22:23], off
	s_waitcnt vmcnt(0)
; __device__ __forceinline__ unsigned cvtpk(float lo, float hi) { f32x2 v = {lo, hi}; bf16x2_t b = __builtin_convertvector(v, bf16x2_t); return __builtin_bit_cast(unsigned, b); }
; __device__ __forceinline__ float shx(float v, int o, int lane) { return __builtin_bit_cast(float, __builtin_amdgcn_ds_bpermute((lane ^ o) << 2, __builtin_bit_cast(int, v))); }
;     __device__ __forceinline__ void operator()(const f32x4 (&acc)[2][2][4][2], const Unit& u, int wv) const {
;     ...
;             for (int bj = 0; bj < 2; ++bj) { const int col = col0 + bj * HALF;
;                 f32x4 v0 = acc[ai][bj][m][0] * rstd, v1 = acc[ai][bj][m][1] * rstd;
;                 if (PP) { const u32x4 g = *(const u32x4*)(PP + row * 1024 + col);
;                     v0[0] = sigmoidf_(v0[0]) * __builtin_bit_cast(float, g.x << 16); v0[1] = sigmoidf_(v0[1]) * __builtin_bit_cast(float, g.x & 0xffff0000u);
;                     v0[2] = sigmoidf_(v0[2]) * __builtin_bit_cast(float, g.y << 16); v0[3] = sigmoidf_(v0[3]) * __builtin_bit_cast(float, g.y & 0xffff0000u);
;                     v1[0] = sigmoidf_(v1[0]) * __builtin_bit_cast(float, g.z << 16); v1[1] = sigmoidf_(v1[1]) * __builtin_bit_cast(float, g.z & 0xffff0000u);
;                     v1[2] = sigmoidf_(v1[2]) * __builtin_bit_cast(float, g.w << 16); v1[3] = sigmoidf_(v1[3]) * __builtin_bit_cast(float, g.w & 0xffff0000u); }
;                 float* xp = X + row * 1024 + col;
;                 v0 += *(const f32x4*)xp; v1 += *(const f32x4*)(xp + 4);
;                 *(f32x4*)xp = v0; *(f32x4*)(xp + 4) = v1;
;                 u32x4 w; w.x = cvtpk(v0[0], v0[1]); w.y = cvtpk(v0[2], v0[3]); w.z = cvtpk(v1[0], v1[1]); w.w = cvtpk(v1[2], v1[3]);
;                 *(u32x4*)(XB + row * 1024 + col) = w;
;                 ssq += ((v0[0] * v0[0] + v0[1] * v0[1]) + (v0[2] * v0[2] + v0[3] * v0[3])) + ((v1[0] * v1[0] + v1[1] * v1[1]) + (v1[2] * v1[2] + v1[3] * v1[3])); }
;             sq[ai][m] = ssq;
;             if (m & 1) asm volatile("" ::: "memory"); }
; #pragma unroll
;         EPI_LOOP_ROWS sq[ai][m] += shx(sq[ai][m], 16, t_ & 63);
; #pragma unroll
;         EPI_LOOP_ROWS sq[ai][m] += shx(sq[ai][m], 32, t_ & 63);
;         if (fq == 0) {
; #pragma unroll
;             EPI_LOOP_ROWS RSout[(size_t)(row0 + ai * HALF + m * 16) * 16 + u.pn * 4 + wc] = sq[ai][m]; }
	v_pk_fma_f32 v[16:17], v[14:15], v[16:17], v[40:41]
	v_pk_fma_f32 v[14:15], v[10:11], v[12:13], v[38:39]
	v_pk_fma_f32 v[10:11], v[18:19], v[20:21], v[30:31]
	v_pk_fma_f32 v[12:13], v[34:35], v[42:43], v[32:33]
	global_store_dwordx4 v[22:23], v[14:17], off
	global_store_dwordx4 v[22:23], v[10:13], off offset:16
	v_cvt_pk_bf16_f32 v18, v14, v15
	v_cvt_pk_bf16_f32 v20, v10, v11
	v_mul_f32_e32 v15, v15, v15
	v_mul_f32_e32 v11, v11, v11
	v_fmac_f32_e32 v15, v14, v14
	v_mul_f32_e32 v14, v17, v17
	v_fmac_f32_e32 v11, v10, v10
	v_mul_f32_e32 v10, v13, v13
	v_fmac_f32_e32 v14, v16, v16
	v_fmac_f32_e32 v10, v12, v12
	v_cvt_pk_bf16_f32 v19, v16, v17
	v_cvt_pk_bf16_f32 v21, v12, v13
	v_add_f32_e32 v14, v15, v14
	v_add_f32_e32 v10, v11, v10
	global_store_dwordx4 v[26:27], v[18:21], off
	v_pk_mul_f32 v[12:13], v[4:5], v[0:1] op_sel_hi:[1,0]
	s_nop 0
	v_add_f32_e32 v18, v14, v10
	v_pk_mul_f32 v[14:15], v[2:3], v[0:1] op_sel_hi:[1,0]
	v_mov_b32_e32 v2, v224
	v_mov_b32_e32 v3, v225
	v_mov_b32_e32 v4, v226
	v_mov_b32_e32 v5, v227
	global_load_dwordx4 v[30:33], v[22:23], off offset:528
	global_load_dwordx4 v[38:41], v[22:23], off offset:512
	v_pk_mul_f32 v[10:11], v[8:9], v[0:1] op_sel_hi:[1,0]
	v_mul_f32_e32 v0, 0xbfb8aa3b, v6
	v_exp_f32_e32 v0, v0
	s_waitcnt vmcnt(2)
	v_lshlrev_b32_e32 v8, 16, v2
	v_add_f32_e32 v0, 1.0, v0
	v_rcp_f32_e32 v6, v0
	v_mul_f32_e32 v0, 0xbfb8aa3b, v7
	v_exp_f32_e32 v0, v0
	v_and_b32_e32 v9, 0xffff0000, v2
	v_lshlrev_b32_e32 v2, 16, v3
	v_and_b32_e32 v3, 0xffff0000, v3
	v_add_f32_e32 v0, 1.0, v0
	v_rcp_f32_e32 v7, v0
	v_mul_f32_e32 v0, 0xbfb8aa3b, v10
	v_exp_f32_e32 v0, v0
	v_lshlrev_b32_e32 v16, 16, v4
	v_and_b32_e32 v17, 0xffff0000, v4
	v_lshlrev_b32_e32 v20, 16, v5
	v_add_f32_e32 v0, 1.0, v0
	v_rcp_f32_e32 v10, v0
	v_mul_f32_e32 v0, 0xbfb8aa3b, v11
	v_exp_f32_e32 v0, v0
	v_and_b32_e32 v21, 0xffff0000, v5
	v_add_f32_e32 v0, 1.0, v0
	v_rcp_f32_e32 v11, v0
	v_mul_f32_e32 v0, 0xbfb8aa3b, v14
	v_exp_f32_e32 v0, v0
	s_waitcnt vmcnt(0)
	v_pk_fma_f32 v[4:5], v[10:11], v[2:3], v[40:41]
	v_pk_fma_f32 v[2:3], v[6:7], v[8:9], v[38:39]
	v_add_f32_e32 v0, 1.0, v0
	v_rcp_f32_e32 v14, v0
	v_mul_f32_e32 v0, 0xbfb8aa3b, v15
	v_exp_f32_e32 v0, v0
	v_cvt_pk_bf16_f32 v10, v2, v3
	v_cvt_pk_bf16_f32 v11, v4, v5
	v_add_f32_e32 v0, 1.0, v0
	v_rcp_f32_e32 v15, v0
	v_mul_f32_e32 v0, 0xbfb8aa3b, v12
	v_exp_f32_e32 v0, v0
	v_pk_fma_f32 v[6:7], v[14:15], v[16:17], v[30:31]
	v_add_f32_e32 v0, 1.0, v0
	v_rcp_f32_e32 v12, v0
	v_mul_f32_e32 v0, 0xbfb8aa3b, v13
	v_exp_f32_e32 v0, v0
	s_nop 0
	v_add_f32_e32 v0, 1.0, v0
	v_rcp_f32_e32 v13, v0
	v_mul_f32_e32 v0, v3, v3
	v_fmac_f32_e32 v0, v2, v2
	v_pk_fma_f32 v[8:9], v[12:13], v[20:21], v[32:33]
	global_store_dwordx4 v[22:23], v[2:5], off offset:512
	global_store_dwordx4 v[22:23], v[6:9], off offset:528
	v_cvt_pk_bf16_f32 v13, v8, v9
	v_mul_f32_e32 v2, v5, v5
	v_fmac_f32_e32 v2, v4, v4
	v_add_f32_e32 v0, v0, v2
	v_mul_f32_e32 v2, v7, v7
	v_mul_f32_e32 v3, v9, v9
	v_fmac_f32_e32 v2, v6, v6
	v_fmac_f32_e32 v3, v8, v8
	v_add_f32_e32 v2, v2, v3
	v_add_f32_e32 v0, v0, v2
	v_add_f32_e32 v8, v18, v0
	v_cvt_pk_bf16_f32 v12, v6, v7
	ds_bpermute_b32 v0, v216, v128
	ds_bpermute_b32 v2, v216, v120
	ds_bpermute_b32 v3, v216, v96
	ds_bpermute_b32 v4, v216, v88
	ds_bpermute_b32 v5, v216, v52
	ds_bpermute_b32 v6, v216, v36
	ds_bpermute_b32 v7, v216, v28
	ds_bpermute_b32 v9, v216, v8
	s_waitcnt lgkmcnt(7)
	v_add_f32_e32 v0, v128, v0
	s_waitcnt lgkmcnt(6)
	v_add_f32_e32 v2, v120, v2
	s_waitcnt lgkmcnt(5)
	v_add_f32_e32 v3, v96, v3
	s_waitcnt lgkmcnt(4)
	v_add_f32_e32 v4, v88, v4
	s_waitcnt lgkmcnt(3)
	v_add_f32_e32 v5, v52, v5
	s_waitcnt lgkmcnt(2)
	v_add_f32_e32 v6, v36, v6
	s_waitcnt lgkmcnt(1)
	v_add_f32_e32 v7, v28, v7
	s_waitcnt lgkmcnt(0)
	v_add_f32_e32 v8, v8, v9
	global_store_dwordx4 v[26:27], v[10:13], off offset:256
	ds_bpermute_b32 v9, v215, v0
	ds_bpermute_b32 v10, v215, v2
	ds_bpermute_b32 v11, v215, v3
	ds_bpermute_b32 v12, v215, v4
	ds_bpermute_b32 v13, v215, v5
	ds_bpermute_b32 v14, v215, v6
	ds_bpermute_b32 v15, v215, v7
	ds_bpermute_b32 v16, v215, v8
	s_and_saveexec_b64 s[4:5], vcc
	s_cbranch_execz .LBB0_146
	s_lshl_b32 s0, s28, 2
	s_ashr_i32 s1, s0, 31
	s_lshl_b64 s[0:1], s[0:1], 2
	s_add_u32 s0, s60, s0
	s_addc_u32 s1, s61, s1
	s_lshl_b32 s10, s49, 2
	s_add_u32 s0, s0, s10
	s_addc_u32 s1, s1, 0
	s_waitcnt lgkmcnt(5)
	v_add_f32_e32 v11, v3, v11
	v_add_f32_e32 v10, v2, v10
	v_add_f32_e32 v0, v0, v9
	v_lshl_add_u64 v[2:3], s[0:1], 0, v[142:143]
	global_store_dword v[2:3], v0, off
	v_lshl_add_u64 v[2:3], s[0:1], 0, v[144:145]
	global_store_dword v[2:3], v10, off
	v_lshl_add_u64 v[2:3], s[0:1], 0, v[146:147]
	s_waitcnt lgkmcnt(4)
	v_add_f32_e32 v4, v4, v12
	global_store_dword v[2:3], v11, off
	v_lshl_add_u64 v[2:3], s[0:1], 0, v[148:149]
	s_waitcnt lgkmcnt(3)
	v_add_f32_e32 v5, v5, v13
	global_store_dword v[2:3], v4, off
	v_lshl_add_u64 v[2:3], s[0:1], 0, v[150:151]
	s_waitcnt lgkmcnt(2)
	v_add_f32_e32 v6, v6, v14
	global_store_dword v[2:3], v5, off
	v_lshl_add_u64 v[2:3], s[0:1], 0, v[152:153]
	s_waitcnt lgkmcnt(1)
	v_add_f32_e32 v7, v7, v15
	global_store_dword v[2:3], v6, off
	v_lshl_add_u64 v[2:3], s[0:1], 0, v[154:155]
	s_waitcnt lgkmcnt(0)
	v_add_f32_e32 v8, v8, v16
	global_store_dword v[2:3], v7, off
	v_lshl_add_u64 v[2:3], s[0:1], 0, v[156:157]
	global_store_dword v[2:3], v8, off
